# multi-unit GEMM phases: the trailing wave group's re-stagger barrier moved from the end of the epilogue to just before its first load phase of the next unit, so both groups run the next-unit decode co
# baseline (speedup 1.0000x reference)
.LBB0_429:
	s_ashr_i32 s27, s26, 31
	s_lshl_b64 s[28:29], s[26:27], 18
	s_cmp_eq_u32 s44, 0
	s_cselect_b32 s9, s79, s83
	s_cselect_b32 s7, s80, s84
	s_cselect_b32 s21, s81, s77
	s_cselect_b32 s27, s82, s85
	s_add_u32 s28, s9, s28
	s_addc_u32 s29, s7, s29
	s_and_b64 s[30:31], s[22:23], exec
	s_cselect_b32 s7, s29, s37
	s_cselect_b32 s9, s28, s36
	s_ashr_i32 s25, s24, 31
	s_lshl_b64 s[30:31], s[24:25], 18
	s_add_u32 s30, s21, s30
	s_addc_u32 s31, s27, s31
	s_and_b64 s[38:39], s[22:23], exec
	s_cselect_b32 s21, s31, s35
	s_cselect_b32 s25, s30, s34
	s_add_u32 s27, s34, 0x100
	s_addc_u32 s45, s35, 0
	s_add_u32 s34, s36, 0x20080
	s_addc_u32 s35, s37, 0
	s_mov_b32 s48, -2
	s_cmp_eq_u32 s99, 0
	s_cbranch_scc1 .Lno_e2_G67
	s_and_b64 s[100:101], exec, s[10:11]
	s_cbranch_scc0 .Lno_e2_G67
	s_barrier
.Lno_e2_G67:
.Lpeel_G67:
	s_add_u32 s36, s34, 0xfffe0080
	s_addc_u32 s37, s35, -1
	s_add_i32 s49, 0, 0x10000
	s_cmp_eq_u32 s48, 4
	s_cselect_b32 s39, s7, s37
	s_cselect_b32 s38, s9, s36
	s_cselect_b32 s37, s21, s45
	s_cselect_b32 s36, s25, s27
	s_add_i32 s61, 0, 0x14000
	v_add_u32_e32 v142, s49, v216
	v_add_u32_e32 v158, s61, v216
	ds_read_b128 v[130:133], v142
	ds_read_b128 v[134:137], v142 offset:1024
	ds_read_b128 v[138:141], v142 offset:2048
	ds_read_b128 v[142:145], v142 offset:3072
	ds_read_b128 v[146:149], v158
	ds_read_b128 v[150:153], v158 offset:1024
	ds_read_b128 v[154:157], v158 offset:2048
	ds_read_b128 v[158:161], v158 offset:3072
	v_lshl_add_u64 v[202:203], s[34:35], 0, v[210:211]
	s_add_i32 m0, s87, 0xc000
	ds_read_b128 v[162:165], v221
	ds_read_b128 v[166:169], v221 offset:1024
	ds_read_b128 v[170:173], v221 offset:2048
	ds_read_b128 v[174:177], v221 offset:3072
	ds_read_b128 v[178:181], v221 offset:4096
	ds_read_b128 v[182:185], v221 offset:5120
	ds_read_b128 v[186:189], v221 offset:6144
	ds_read_b128 v[190:193], v221 offset:7168
	global_load_lds_dwordx4 v[202:203], off
	v_lshl_add_u64 v[202:203], s[34:35], 0, v[208:209]
	s_add_i32 m0, s87, 0xe000
	s_nop 0
	global_load_lds_dwordx4 v[202:203], off
	s_waitcnt vmcnt(8)
	s_waitcnt lgkmcnt(0)
	s_barrier
	s_setprio 1
	s_waitcnt lgkmcnt(0)
	v_mfma_f32_16x16x32_bf16 v[126:129], v[130:133], v[162:165], 0
	v_mfma_f32_16x16x32_bf16 v[122:125], v[138:141], v[162:165], 0
	v_mfma_f32_16x16x32_bf16 v[110:113], v[130:133], v[170:173], 0
	v_mfma_f32_16x16x32_bf16 v[106:109], v[138:141], v[170:173], 0
	v_mfma_f32_16x16x32_bf16 v[94:97], v[130:133], v[178:181], 0
	v_mfma_f32_16x16x32_bf16 v[90:93], v[138:141], v[178:181], 0
	v_mfma_f32_16x16x32_bf16 v[78:81], v[130:133], v[186:189], 0
	v_mfma_f32_16x16x32_bf16 v[74:77], v[138:141], v[186:189], 0
	v_mfma_f32_16x16x32_bf16 v[126:129], v[134:137], v[166:169], v[126:129]
	v_mfma_f32_16x16x32_bf16 v[122:125], v[142:145], v[166:169], v[122:125]
	v_mfma_f32_16x16x32_bf16 v[110:113], v[134:137], v[174:177], v[110:113]
	v_mfma_f32_16x16x32_bf16 v[106:109], v[142:145], v[174:177], v[106:109]
	v_mfma_f32_16x16x32_bf16 v[94:97], v[134:137], v[182:185], v[94:97]
	v_mfma_f32_16x16x32_bf16 v[90:93], v[142:145], v[182:185], v[90:93]
	v_mfma_f32_16x16x32_bf16 v[78:81], v[134:137], v[190:193], v[78:81]
	v_mfma_f32_16x16x32_bf16 v[74:77], v[142:145], v[190:193], v[74:77]
	s_setprio 0
	s_setprio 1
	v_mfma_f32_16x16x32_bf16 v[118:121], v[146:149], v[162:165], 0
	v_mfma_f32_16x16x32_bf16 v[114:117], v[154:157], v[162:165], 0
	v_mfma_f32_16x16x32_bf16 v[102:105], v[146:149], v[170:173], 0
	v_mfma_f32_16x16x32_bf16 v[98:101], v[154:157], v[170:173], 0
	v_mfma_f32_16x16x32_bf16 v[86:89], v[146:149], v[178:181], 0
	v_mfma_f32_16x16x32_bf16 v[82:85], v[154:157], v[178:181], 0
	v_mfma_f32_16x16x32_bf16 v[70:73], v[146:149], v[186:189], 0
	v_mfma_f32_16x16x32_bf16 v[66:69], v[154:157], v[186:189], 0
	v_mfma_f32_16x16x32_bf16 v[118:121], v[150:153], v[166:169], v[118:121]
	v_mfma_f32_16x16x32_bf16 v[114:117], v[158:161], v[166:169], v[114:117]
	v_mfma_f32_16x16x32_bf16 v[102:105], v[150:153], v[174:177], v[102:105]
	v_mfma_f32_16x16x32_bf16 v[98:101], v[158:161], v[174:177], v[98:101]
	v_mfma_f32_16x16x32_bf16 v[86:89], v[150:153], v[182:185], v[86:89]
	v_mfma_f32_16x16x32_bf16 v[82:85], v[158:161], v[182:185], v[82:85]
	v_mfma_f32_16x16x32_bf16 v[70:73], v[150:153], v[190:193], v[70:73]
	v_mfma_f32_16x16x32_bf16 v[66:69], v[158:161], v[190:193], v[66:69]
	s_setprio 0
	s_barrier
	s_add_i32 s49, s49, s86
	v_lshl_add_u64 v[202:203], s[36:37], 0, v[194:195]
	s_mov_b32 m0, s49
	ds_read_b128 v[162:165], v221 offset:16384
	ds_read_b128 v[166:169], v221 offset:17408
	ds_read_b128 v[170:173], v221 offset:18432
	ds_read_b128 v[174:177], v221 offset:19456
	ds_read_b128 v[178:181], v221 offset:20480
	ds_read_b128 v[182:185], v221 offset:21504
	ds_read_b128 v[186:189], v221 offset:22528
	ds_read_b128 v[190:193], v221 offset:23552
	global_load_lds_dwordx4 v[202:203], off
	s_add_i32 m0, s49, 0x2000
	s_add_u32 s94, s36, 0x20000
	v_lshl_add_u64 v[204:205], s[36:37], 0, v[196:197]
	s_addc_u32 s95, s37, 0
	s_add_i32 s49, s61, s86
	global_load_lds_dwordx4 v[204:205], off
	v_lshl_add_u64 v[206:207], s[94:95], 0, v[194:195]
	s_mov_b32 m0, s49
	v_lshl_add_u64 v[222:223], s[38:39], 0, v[196:197]
	global_load_lds_dwordx4 v[206:207], off
	v_lshl_add_u64 v[206:207], s[94:95], 0, v[196:197]
	s_add_i32 m0, s49, 0x2000
	s_nop 0
	global_load_lds_dwordx4 v[206:207], off
	v_lshl_add_u64 v[206:207], s[38:39], 0, v[194:195]
	s_mov_b32 m0, s87
	s_nop 0
	global_load_lds_dwordx4 v[206:207], off
	s_mov_b32 m0, s68
	s_nop 0
	global_load_lds_dwordx4 v[222:223], off
	s_waitcnt vmcnt(8)
	s_waitcnt lgkmcnt(0)
	s_barrier
	s_setprio 1
	s_waitcnt lgkmcnt(0)
	v_mfma_f32_16x16x32_bf16 v[62:65], v[130:133], v[162:165], 0
	v_mfma_f32_16x16x32_bf16 v[58:61], v[138:141], v[162:165], 0
	v_mfma_f32_16x16x32_bf16 v[46:49], v[130:133], v[170:173], 0
	v_mfma_f32_16x16x32_bf16 v[42:45], v[138:141], v[170:173], 0
	v_mfma_f32_16x16x32_bf16 v[30:33], v[130:133], v[178:181], 0
	v_mfma_f32_16x16x32_bf16 v[26:29], v[138:141], v[178:181], 0
	v_mfma_f32_16x16x32_bf16 v[14:17], v[130:133], v[186:189], 0
	v_mfma_f32_16x16x32_bf16 v[10:13], v[138:141], v[186:189], 0
	v_mfma_f32_16x16x32_bf16 v[62:65], v[134:137], v[166:169], v[62:65]
	v_mfma_f32_16x16x32_bf16 v[58:61], v[142:145], v[166:169], v[58:61]
	v_mfma_f32_16x16x32_bf16 v[46:49], v[134:137], v[174:177], v[46:49]
	v_mfma_f32_16x16x32_bf16 v[42:45], v[142:145], v[174:177], v[42:45]
	v_mfma_f32_16x16x32_bf16 v[30:33], v[134:137], v[182:185], v[30:33]
	v_mfma_f32_16x16x32_bf16 v[26:29], v[142:145], v[182:185], v[26:29]
	v_mfma_f32_16x16x32_bf16 v[14:17], v[134:137], v[190:193], v[14:17]
	v_mfma_f32_16x16x32_bf16 v[10:13], v[142:145], v[190:193], v[10:13]
	s_setprio 0
	s_setprio 1
	v_mfma_f32_16x16x32_bf16 v[54:57], v[146:149], v[162:165], 0
	v_mfma_f32_16x16x32_bf16 v[50:53], v[154:157], v[162:165], 0
	v_mfma_f32_16x16x32_bf16 v[38:41], v[146:149], v[170:173], 0
	v_mfma_f32_16x16x32_bf16 v[34:37], v[154:157], v[170:173], 0
	v_mfma_f32_16x16x32_bf16 v[22:25], v[146:149], v[178:181], 0
	v_mfma_f32_16x16x32_bf16 v[18:21], v[154:157], v[178:181], 0
	v_mfma_f32_16x16x32_bf16 v[6:9], v[146:149], v[186:189], 0
	v_mfma_f32_16x16x32_bf16 v[2:5], v[154:157], v[186:189], 0
	v_mfma_f32_16x16x32_bf16 v[54:57], v[150:153], v[166:169], v[54:57]
	v_mfma_f32_16x16x32_bf16 v[50:53], v[158:161], v[166:169], v[50:53]
	v_mfma_f32_16x16x32_bf16 v[38:41], v[150:153], v[174:177], v[38:41]
	v_mfma_f32_16x16x32_bf16 v[34:37], v[158:161], v[174:177], v[34:37]
	v_mfma_f32_16x16x32_bf16 v[22:25], v[150:153], v[182:185], v[22:25]
	v_mfma_f32_16x16x32_bf16 v[18:21], v[158:161], v[182:185], v[18:21]
	v_mfma_f32_16x16x32_bf16 v[6:9], v[150:153], v[190:193], v[6:9]
	v_mfma_f32_16x16x32_bf16 v[2:5], v[158:161], v[190:193], v[2:5]
	s_setprio 0
	s_barrier
	s_add_i32 s49, 0, 0x18000
	s_add_i32 s61, 0, 0x1c000
	v_add_u32_e32 v142, s49, v216
	v_add_u32_e32 v158, s61, v216
	ds_read_b128 v[130:133], v142
	ds_read_b128 v[134:137], v142 offset:1024
	ds_read_b128 v[138:141], v142 offset:2048
	ds_read_b128 v[142:145], v142 offset:3072
	ds_read_b128 v[146:149], v158
	ds_read_b128 v[150:153], v158 offset:1024
	ds_read_b128 v[154:157], v158 offset:2048
	ds_read_b128 v[158:161], v158 offset:3072
	s_add_u32 s38, s38, 0x20000
	s_addc_u32 s39, s39, 0
	s_mov_b32 m0, s69
	v_lshl_add_u64 v[226:227], s[38:39], 0, v[194:195]
	ds_read_b128 v[162:165], v221 offset:32768
	ds_read_b128 v[166:169], v221 offset:33792
	ds_read_b128 v[170:173], v221 offset:34816
	ds_read_b128 v[174:177], v221 offset:35840
	ds_read_b128 v[178:181], v221 offset:36864
	ds_read_b128 v[182:185], v221 offset:37888
	ds_read_b128 v[186:189], v221 offset:38912
	ds_read_b128 v[190:193], v221 offset:39936
	global_load_lds_dwordx4 v[226:227], off
	v_lshl_add_u64 v[226:227], s[38:39], 0, v[196:197]
	s_mov_b32 m0, s70
	s_nop 0
	global_load_lds_dwordx4 v[226:227], off
	s_waitcnt vmcnt(8)
	s_waitcnt lgkmcnt(0)
	s_barrier
	s_setprio 1
	s_waitcnt lgkmcnt(0)
	v_mfma_f32_16x16x32_bf16 v[126:129], v[130:133], v[162:165], v[126:129]
	v_mfma_f32_16x16x32_bf16 v[122:125], v[138:141], v[162:165], v[122:125]
	v_mfma_f32_16x16x32_bf16 v[110:113], v[130:133], v[170:173], v[110:113]
	v_mfma_f32_16x16x32_bf16 v[106:109], v[138:141], v[170:173], v[106:109]
	v_mfma_f32_16x16x32_bf16 v[94:97], v[130:133], v[178:181], v[94:97]
	v_mfma_f32_16x16x32_bf16 v[90:93], v[138:141], v[178:181], v[90:93]
	v_mfma_f32_16x16x32_bf16 v[78:81], v[130:133], v[186:189], v[78:81]
	v_mfma_f32_16x16x32_bf16 v[74:77], v[138:141], v[186:189], v[74:77]
	v_mfma_f32_16x16x32_bf16 v[126:129], v[134:137], v[166:169], v[126:129]
	v_mfma_f32_16x16x32_bf16 v[122:125], v[142:145], v[166:169], v[122:125]
	v_mfma_f32_16x16x32_bf16 v[110:113], v[134:137], v[174:177], v[110:113]
	v_mfma_f32_16x16x32_bf16 v[106:109], v[142:145], v[174:177], v[106:109]
	v_mfma_f32_16x16x32_bf16 v[94:97], v[134:137], v[182:185], v[94:97]
	v_mfma_f32_16x16x32_bf16 v[90:93], v[142:145], v[182:185], v[90:93]
	v_mfma_f32_16x16x32_bf16 v[78:81], v[134:137], v[190:193], v[78:81]
	v_mfma_f32_16x16x32_bf16 v[74:77], v[142:145], v[190:193], v[74:77]
	s_setprio 0
	s_setprio 1
	v_mfma_f32_16x16x32_bf16 v[118:121], v[146:149], v[162:165], v[118:121]
	v_mfma_f32_16x16x32_bf16 v[114:117], v[154:157], v[162:165], v[114:117]
	v_mfma_f32_16x16x32_bf16 v[102:105], v[146:149], v[170:173], v[102:105]
	v_mfma_f32_16x16x32_bf16 v[98:101], v[154:157], v[170:173], v[98:101]
	v_mfma_f32_16x16x32_bf16 v[86:89], v[146:149], v[178:181], v[86:89]
	v_mfma_f32_16x16x32_bf16 v[82:85], v[154:157], v[178:181], v[82:85]
	v_mfma_f32_16x16x32_bf16 v[70:73], v[146:149], v[186:189], v[70:73]
	v_mfma_f32_16x16x32_bf16 v[66:69], v[154:157], v[186:189], v[66:69]
	v_mfma_f32_16x16x32_bf16 v[118:121], v[150:153], v[166:169], v[118:121]
	v_mfma_f32_16x16x32_bf16 v[114:117], v[158:161], v[166:169], v[114:117]
	v_mfma_f32_16x16x32_bf16 v[102:105], v[150:153], v[174:177], v[102:105]
	v_mfma_f32_16x16x32_bf16 v[98:101], v[158:161], v[174:177], v[98:101]
	v_mfma_f32_16x16x32_bf16 v[86:89], v[150:153], v[182:185], v[86:89]
	v_mfma_f32_16x16x32_bf16 v[82:85], v[158:161], v[182:185], v[82:85]
	v_mfma_f32_16x16x32_bf16 v[70:73], v[150:153], v[190:193], v[70:73]
	v_mfma_f32_16x16x32_bf16 v[66:69], v[158:161], v[190:193], v[66:69]
	s_setprio 0
	s_barrier
	s_add_i32 s38, s49, s86
	v_lshl_add_u64 v[202:203], v[202:203], 0, s[54:55]
	s_mov_b32 m0, s38
	ds_read_b128 v[162:165], v221 offset:49152
	ds_read_b128 v[166:169], v221 offset:50176
	ds_read_b128 v[170:173], v221 offset:51200
	ds_read_b128 v[174:177], v221 offset:52224
	ds_read_b128 v[178:181], v221 offset:53248
	ds_read_b128 v[182:185], v221 offset:54272
	ds_read_b128 v[186:189], v221 offset:55296
	ds_read_b128 v[190:193], v221 offset:56320
	global_load_lds_dwordx4 v[202:203], off
	s_add_i32 m0, s38, 0x2000
	s_add_u32 s36, s36, 0x20080
	v_lshl_add_u64 v[202:203], v[204:205], 0, s[54:55]
	s_addc_u32 s37, s37, 0
	s_add_i32 s38, s61, s86
	global_load_lds_dwordx4 v[202:203], off
	v_lshl_add_u64 v[202:203], s[36:37], 0, v[194:195]
	s_mov_b32 m0, s38
	s_nop 0
	global_load_lds_dwordx4 v[202:203], off
	v_lshl_add_u64 v[202:203], s[36:37], 0, v[196:197]
	s_add_i32 m0, s38, 0x2000
	s_nop 0
	global_load_lds_dwordx4 v[202:203], off
	v_lshl_add_u64 v[202:203], v[206:207], 0, s[54:55]
	s_mov_b32 m0, s73
	s_nop 0
	global_load_lds_dwordx4 v[202:203], off
	v_lshl_add_u64 v[202:203], v[222:223], 0, s[54:55]
	s_mov_b32 m0, s89
	s_nop 0
	global_load_lds_dwordx4 v[202:203], off
	s_waitcnt vmcnt(8)
	s_waitcnt lgkmcnt(0)
	s_barrier
	s_setprio 1
	s_waitcnt lgkmcnt(0)
	v_mfma_f32_16x16x32_bf16 v[62:65], v[130:133], v[162:165], v[62:65]
	v_mfma_f32_16x16x32_bf16 v[58:61], v[138:141], v[162:165], v[58:61]
	v_mfma_f32_16x16x32_bf16 v[46:49], v[130:133], v[170:173], v[46:49]
	v_mfma_f32_16x16x32_bf16 v[42:45], v[138:141], v[170:173], v[42:45]
	v_mfma_f32_16x16x32_bf16 v[30:33], v[130:133], v[178:181], v[30:33]
	v_mfma_f32_16x16x32_bf16 v[26:29], v[138:141], v[178:181], v[26:29]
	v_mfma_f32_16x16x32_bf16 v[14:17], v[130:133], v[186:189], v[14:17]
	v_mfma_f32_16x16x32_bf16 v[10:13], v[138:141], v[186:189], v[10:13]
	v_mfma_f32_16x16x32_bf16 v[62:65], v[134:137], v[166:169], v[62:65]
	v_mfma_f32_16x16x32_bf16 v[58:61], v[142:145], v[166:169], v[58:61]
	v_mfma_f32_16x16x32_bf16 v[46:49], v[134:137], v[174:177], v[46:49]
	v_mfma_f32_16x16x32_bf16 v[42:45], v[142:145], v[174:177], v[42:45]
	v_mfma_f32_16x16x32_bf16 v[30:33], v[134:137], v[182:185], v[30:33]
	v_mfma_f32_16x16x32_bf16 v[26:29], v[142:145], v[182:185], v[26:29]
	v_mfma_f32_16x16x32_bf16 v[14:17], v[134:137], v[190:193], v[14:17]
	v_mfma_f32_16x16x32_bf16 v[10:13], v[142:145], v[190:193], v[10:13]
	s_setprio 0
	s_setprio 1
	v_mfma_f32_16x16x32_bf16 v[54:57], v[146:149], v[162:165], v[54:57]
	v_mfma_f32_16x16x32_bf16 v[50:53], v[154:157], v[162:165], v[50:53]
	v_mfma_f32_16x16x32_bf16 v[38:41], v[146:149], v[170:173], v[38:41]
	v_mfma_f32_16x16x32_bf16 v[34:37], v[154:157], v[170:173], v[34:37]
	v_mfma_f32_16x16x32_bf16 v[22:25], v[146:149], v[178:181], v[22:25]
	v_mfma_f32_16x16x32_bf16 v[18:21], v[154:157], v[178:181], v[18:21]
	v_mfma_f32_16x16x32_bf16 v[6:9], v[146:149], v[186:189], v[6:9]
	v_mfma_f32_16x16x32_bf16 v[2:5], v[154:157], v[186:189], v[2:5]
	v_mfma_f32_16x16x32_bf16 v[54:57], v[150:153], v[166:169], v[54:57]
	v_mfma_f32_16x16x32_bf16 v[50:53], v[158:161], v[166:169], v[50:53]
	v_mfma_f32_16x16x32_bf16 v[38:41], v[150:153], v[174:177], v[38:41]
	v_mfma_f32_16x16x32_bf16 v[34:37], v[158:161], v[174:177], v[34:37]
	v_mfma_f32_16x16x32_bf16 v[22:25], v[150:153], v[182:185], v[22:25]
	v_mfma_f32_16x16x32_bf16 v[18:21], v[158:161], v[182:185], v[18:21]
	v_mfma_f32_16x16x32_bf16 v[6:9], v[150:153], v[190:193], v[6:9]
	v_mfma_f32_16x16x32_bf16 v[2:5], v[158:161], v[190:193], v[2:5]
	s_setprio 0
	s_barrier
	s_add_i32 s48, s48, 2
	s_add_u32 s27, s27, 0x100
	s_addc_u32 s45, s45, 0
	s_add_u32 s34, s34, 0x100
	s_addc_u32 s35, s35, 0
	s_cmp_gt_u32 s48, 5
	s_cbranch_scc1 .Lpeel_exit_G67

.LBB0_453:
	s_waitcnt vmcnt(0)
	v_cndmask_b32_e64 v207, v191, 0, s[34:35]
	v_cndmask_b32_e64 v206, v190, 0, s[34:35]
	v_cndmask_b32_e64 v205, v187, 1.0, s[34:35]
	v_cndmask_b32_e64 v204, v186, 1.0, s[34:35]
	v_cndmask_b32_e64 v223, v193, 0, s[34:35]
	v_cndmask_b32_e64 v222, v192, 0, s[34:35]
	v_pk_mul_f32 v[230:231], v[122:123], v[206:207]
	v_cndmask_b32_e64 v203, v189, 1.0, s[34:35]
	v_cndmask_b32_e64 v202, v188, 1.0, s[34:35]
	v_pk_mul_f32 v[228:229], v[124:125], v[222:223]
	v_pk_fma_f32 v[230:231], v[126:127], v[204:205], v[230:231] neg_lo:[0,0,1] neg_hi:[0,0,1]
	v_pk_mul_f32 v[126:127], v[126:127], v[206:207]
	v_pk_fma_f32 v[228:229], v[128:129], v[202:203], v[228:229] neg_lo:[0,0,1] neg_hi:[0,0,1]
	v_pk_mul_f32 v[128:129], v[128:129], v[222:223]
	v_pk_fma_f32 v[122:123], v[122:123], v[204:205], v[126:127]
	v_pk_fma_f32 v[124:125], v[124:125], v[202:203], v[128:129]
	v_pk_mul_f32 v[122:123], v[122:123], s[62:63] op_sel_hi:[1,0]
	v_or_b32_e32 v226, s21, v214
	v_pk_mul_f32 v[228:229], v[228:229], s[62:63] op_sel_hi:[1,0]
	v_pk_mul_f32 v[230:231], v[230:231], s[62:63] op_sel_hi:[1,0]
	v_pk_mul_f32 v[128:129], v[124:125], s[62:63] op_sel_hi:[1,0]
	v_cvt_pk_bf16_f32 v124, v230, v231
	v_cvt_pk_bf16_f32 v125, v228, v229
	v_cvt_pk_bf16_f32 v126, v122, v123
	v_mov_b64_e32 v[122:123], s[14:15]
	s_ashr_i32 s37, s36, 31
	v_cvt_pk_bf16_f32 v127, v128, v129
	v_mad_i64_i32 v[128:129], s[6:7], v226, s96, v[122:123]
	s_lshl_b64 s[6:7], s[36:37], 1
	s_nop 0
	v_lshl_add_u64 v[128:129], v[128:129], 0, s[6:7]
	s_mov_b32 s21, s50
	v_lshl_add_u64 v[128:129], v[128:129], 0, s[20:21]
	v_lshl_add_u64 v[128:129], v[128:129], 0, v[0:1]
	v_mov_b32_e32 v213, v1
	s_cmp_eq_u32 s25, 0
	s_nop 1
	v_permlane16_swap_b32 v124, v126
	v_permlane16_swap_b32 v125, v127
	s_nop 1
	v_lshl_add_u64 v[128:129], v[128:129], 0, v[212:213]
	s_cselect_b64 s[8:9], -1, 0
	global_store_dwordx4 v[128:129], v[124:127], off
	v_mov_b64_e32 v[230:231], v[234:235]
	s_nop 0
	v_cndmask_b32_e64 v125, v189, 1.0, s[8:9]
	v_cndmask_b32_e64 v124, v188, 1.0, s[8:9]
	v_cndmask_b32_e64 v127, v187, 1.0, s[8:9]
	v_cndmask_b32_e64 v126, v186, 1.0, s[8:9]
	v_cndmask_b32_e64 v187, v191, 0, s[8:9]
	v_cndmask_b32_e64 v186, v190, 0, s[8:9]
	v_cndmask_b32_e64 v189, v193, 0, s[8:9]
	v_cndmask_b32_e64 v188, v192, 0, s[8:9]
	v_pk_mul_f32 v[190:191], v[116:117], v[188:189]
	v_pk_mul_f32 v[192:193], v[114:115], v[186:187]
	v_pk_fma_f32 v[190:191], v[120:121], v[124:125], v[190:191] neg_lo:[0,0,1] neg_hi:[0,0,1]
	v_pk_fma_f32 v[192:193], v[118:119], v[126:127], v[192:193] neg_lo:[0,0,1] neg_hi:[0,0,1]
	v_pk_mul_f32 v[120:121], v[120:121], v[188:189]
	v_pk_mul_f32 v[118:119], v[118:119], v[186:187]
	v_pk_fma_f32 v[116:117], v[116:117], v[124:125], v[120:121]
	v_pk_fma_f32 v[114:115], v[114:115], v[126:127], v[118:119]
	v_pk_mul_f32 v[118:119], v[116:117], s[62:63] op_sel_hi:[1,0]
	v_pk_mul_f32 v[116:117], v[114:115], s[62:63] op_sel_hi:[1,0]
	v_pk_mul_f32 v[190:191], v[190:191], s[62:63] op_sel_hi:[1,0]
	v_pk_mul_f32 v[192:193], v[192:193], s[62:63] op_sel_hi:[1,0]
	v_cndmask_b32_e64 v121, v181, 0, s[34:35]
	v_cvt_pk_bf16_f32 v114, v192, v193
	v_cvt_pk_bf16_f32 v115, v190, v191
	v_cvt_pk_bf16_f32 v116, v116, v117
	v_cvt_pk_bf16_f32 v117, v118, v119
	v_cndmask_b32_e64 v119, v179, 0, s[34:35]
	s_nop 1
	v_permlane16_swap_b32 v114, v116
	v_permlane16_swap_b32 v115, v117
	s_nop 1
	v_cndmask_b32_e64 v118, v178, 0, s[34:35]
	v_cndmask_b32_e64 v120, v180, 0, s[34:35]
	global_store_dwordx4 v[128:129], v[114:117], off offset:256
	v_pk_mul_f32 v[124:125], v[108:109], v[120:121]
	v_pk_mul_f32 v[126:127], v[106:107], v[118:119]
	v_cndmask_b32_e64 v115, v185, 1.0, s[34:35]
	v_cndmask_b32_e64 v114, v184, 1.0, s[34:35]
	v_cndmask_b32_e64 v117, v183, 1.0, s[34:35]
	v_cndmask_b32_e64 v116, v182, 1.0, s[34:35]
	v_pk_fma_f32 v[126:127], v[110:111], v[116:117], v[126:127] neg_lo:[0,0,1] neg_hi:[0,0,1]
	v_pk_fma_f32 v[124:125], v[112:113], v[114:115], v[124:125] neg_lo:[0,0,1] neg_hi:[0,0,1]
	v_pk_mul_f32 v[112:113], v[112:113], v[120:121]
	v_pk_mul_f32 v[110:111], v[110:111], v[118:119]
	v_pk_fma_f32 v[108:109], v[108:109], v[114:115], v[112:113]
	v_pk_fma_f32 v[106:107], v[106:107], v[116:117], v[110:111]
	v_or_b32_e32 v128, 16, v226
	v_pk_mul_f32 v[110:111], v[108:109], s[62:63] op_sel_hi:[1,0]
	v_pk_mul_f32 v[108:109], v[106:107], s[62:63] op_sel_hi:[1,0]
	v_pk_mul_f32 v[124:125], v[124:125], s[62:63] op_sel_hi:[1,0]
	v_pk_mul_f32 v[126:127], v[126:127], s[62:63] op_sel_hi:[1,0]
	v_cndmask_b32_e64 v113, v179, 0, s[8:9]
	v_cvt_pk_bf16_f32 v106, v126, v127
	v_cvt_pk_bf16_f32 v107, v124, v125
	v_cvt_pk_bf16_f32 v108, v108, v109
	v_cvt_pk_bf16_f32 v109, v110, v111
	v_mad_i64_i32 v[110:111], s[36:37], v128, s96, v[122:123]
	v_lshl_add_u64 v[110:111], v[110:111], 0, s[6:7]
	v_lshl_add_u64 v[110:111], v[110:111], 0, s[20:21]
	v_lshl_add_u64 v[110:111], v[110:111], 0, v[0:1]
	s_nop 1
	v_permlane16_swap_b32 v106, v108
	v_permlane16_swap_b32 v107, v109
	s_nop 1
	v_lshl_add_u64 v[110:111], v[110:111], 0, v[212:213]
	v_cndmask_b32_e64 v112, v178, 0, s[8:9]
	v_cndmask_b32_e64 v115, v181, 0, s[8:9]
	v_cndmask_b32_e64 v114, v180, 0, s[8:9]
	global_store_dwordx4 v[110:111], v[106:109], off
	v_pk_mul_f32 v[116:117], v[100:101], v[114:115]
	v_pk_mul_f32 v[118:119], v[98:99], v[112:113]
	v_cndmask_b32_e64 v107, v185, 1.0, s[8:9]
	v_cndmask_b32_e64 v106, v184, 1.0, s[8:9]
	v_cndmask_b32_e64 v109, v183, 1.0, s[8:9]
	v_cndmask_b32_e64 v108, v182, 1.0, s[8:9]
	v_pk_fma_f32 v[118:119], v[102:103], v[108:109], v[118:119] neg_lo:[0,0,1] neg_hi:[0,0,1]
	v_pk_fma_f32 v[116:117], v[104:105], v[106:107], v[116:117] neg_lo:[0,0,1] neg_hi:[0,0,1]
	v_pk_mul_f32 v[104:105], v[104:105], v[114:115]
	v_pk_mul_f32 v[102:103], v[102:103], v[112:113]
	v_pk_fma_f32 v[100:101], v[100:101], v[106:107], v[104:105]
	v_pk_fma_f32 v[98:99], v[98:99], v[108:109], v[102:103]
	v_pk_mul_f32 v[102:103], v[100:101], s[62:63] op_sel_hi:[1,0]
	v_pk_mul_f32 v[100:101], v[98:99], s[62:63] op_sel_hi:[1,0]
	v_pk_mul_f32 v[116:117], v[116:117], s[62:63] op_sel_hi:[1,0]
	v_pk_mul_f32 v[118:119], v[118:119], s[62:63] op_sel_hi:[1,0]
	v_cndmask_b32_e64 v105, v177, 0, s[34:35]
	v_cvt_pk_bf16_f32 v98, v118, v119
	v_cvt_pk_bf16_f32 v99, v116, v117
	v_cvt_pk_bf16_f32 v100, v100, v101
	v_cvt_pk_bf16_f32 v101, v102, v103
	v_cndmask_b32_e64 v103, v175, 0, s[34:35]
	s_nop 1
	v_permlane16_swap_b32 v98, v100
	v_permlane16_swap_b32 v99, v101
	s_nop 1
	v_cndmask_b32_e64 v102, v174, 0, s[34:35]
	v_cndmask_b32_e64 v104, v176, 0, s[34:35]
	global_store_dwordx4 v[110:111], v[98:101], off offset:256
	v_pk_mul_f32 v[106:107], v[92:93], v[104:105]
	v_pk_mul_f32 v[108:109], v[90:91], v[102:103]
	v_cndmask_b32_e64 v99, v173, 1.0, s[34:35]
	v_cndmask_b32_e64 v98, v172, 1.0, s[34:35]
	v_cndmask_b32_e64 v101, v171, 1.0, s[34:35]
	v_cndmask_b32_e64 v100, v170, 1.0, s[34:35]
	v_pk_fma_f32 v[108:109], v[94:95], v[100:101], v[108:109] neg_lo:[0,0,1] neg_hi:[0,0,1]
	v_pk_fma_f32 v[106:107], v[96:97], v[98:99], v[106:107] neg_lo:[0,0,1] neg_hi:[0,0,1]
	v_pk_mul_f32 v[96:97], v[96:97], v[104:105]
	v_pk_mul_f32 v[94:95], v[94:95], v[102:103]
	v_pk_fma_f32 v[92:93], v[92:93], v[98:99], v[96:97]
	v_pk_fma_f32 v[90:91], v[90:91], v[100:101], v[94:95]
	v_or_b32_e32 v110, 32, v226
	v_pk_mul_f32 v[94:95], v[92:93], s[62:63] op_sel_hi:[1,0]
	v_pk_mul_f32 v[92:93], v[90:91], s[62:63] op_sel_hi:[1,0]
	v_pk_mul_f32 v[106:107], v[106:107], s[62:63] op_sel_hi:[1,0]
	v_pk_mul_f32 v[108:109], v[108:109], s[62:63] op_sel_hi:[1,0]
	v_cndmask_b32_e64 v97, v175, 0, s[8:9]
	v_cvt_pk_bf16_f32 v90, v108, v109
	v_cvt_pk_bf16_f32 v91, v106, v107
	v_cvt_pk_bf16_f32 v92, v92, v93
	v_cvt_pk_bf16_f32 v93, v94, v95
	v_mad_i64_i32 v[94:95], s[36:37], v110, s96, v[122:123]
	v_lshl_add_u64 v[94:95], v[94:95], 0, s[6:7]
	v_lshl_add_u64 v[94:95], v[94:95], 0, s[20:21]
	v_lshl_add_u64 v[94:95], v[94:95], 0, v[0:1]
	s_nop 1
	v_permlane16_swap_b32 v90, v92
	v_permlane16_swap_b32 v91, v93
	s_nop 1
	v_lshl_add_u64 v[94:95], v[94:95], 0, v[212:213]
	v_cndmask_b32_e64 v96, v174, 0, s[8:9]
	v_cndmask_b32_e64 v99, v177, 0, s[8:9]
	v_cndmask_b32_e64 v98, v176, 0, s[8:9]
	global_store_dwordx4 v[94:95], v[90:93], off
	v_pk_mul_f32 v[100:101], v[84:85], v[98:99]
	v_pk_mul_f32 v[102:103], v[82:83], v[96:97]
	v_cndmask_b32_e64 v91, v173, 1.0, s[8:9]
	v_cndmask_b32_e64 v90, v172, 1.0, s[8:9]
	v_cndmask_b32_e64 v93, v171, 1.0, s[8:9]
	v_cndmask_b32_e64 v92, v170, 1.0, s[8:9]
	v_pk_fma_f32 v[102:103], v[86:87], v[92:93], v[102:103] neg_lo:[0,0,1] neg_hi:[0,0,1]
	v_pk_fma_f32 v[100:101], v[88:89], v[90:91], v[100:101] neg_lo:[0,0,1] neg_hi:[0,0,1]
	v_pk_mul_f32 v[88:89], v[88:89], v[98:99]
	v_pk_mul_f32 v[86:87], v[86:87], v[96:97]
	v_pk_fma_f32 v[84:85], v[84:85], v[90:91], v[88:89]
	v_pk_fma_f32 v[82:83], v[82:83], v[92:93], v[86:87]
	v_pk_mul_f32 v[86:87], v[84:85], s[62:63] op_sel_hi:[1,0]
	v_pk_mul_f32 v[84:85], v[82:83], s[62:63] op_sel_hi:[1,0]
	v_pk_mul_f32 v[100:101], v[100:101], s[62:63] op_sel_hi:[1,0]
	v_pk_mul_f32 v[102:103], v[102:103], s[62:63] op_sel_hi:[1,0]
	v_cndmask_b32_e64 v89, v165, 0, s[34:35]
	v_cvt_pk_bf16_f32 v82, v102, v103
	v_cvt_pk_bf16_f32 v83, v100, v101
	v_cvt_pk_bf16_f32 v84, v84, v85
	v_cvt_pk_bf16_f32 v85, v86, v87
	v_cndmask_b32_e64 v87, v163, 0, s[34:35]
	s_nop 1
	v_permlane16_swap_b32 v82, v84
	v_permlane16_swap_b32 v83, v85
	s_nop 1
	v_cndmask_b32_e64 v86, v162, 0, s[34:35]
	v_cndmask_b32_e64 v88, v164, 0, s[34:35]
	global_store_dwordx4 v[94:95], v[82:85], off offset:256
	v_pk_mul_f32 v[90:91], v[76:77], v[88:89]
	v_pk_mul_f32 v[92:93], v[74:75], v[86:87]
	v_cndmask_b32_e64 v83, v169, 1.0, s[34:35]
	v_cndmask_b32_e64 v82, v168, 1.0, s[34:35]
	v_cndmask_b32_e64 v85, v167, 1.0, s[34:35]
	v_cndmask_b32_e64 v84, v166, 1.0, s[34:35]
	v_pk_fma_f32 v[92:93], v[78:79], v[84:85], v[92:93] neg_lo:[0,0,1] neg_hi:[0,0,1]
	v_pk_fma_f32 v[90:91], v[80:81], v[82:83], v[90:91] neg_lo:[0,0,1] neg_hi:[0,0,1]
	v_pk_mul_f32 v[80:81], v[80:81], v[88:89]
	v_pk_mul_f32 v[78:79], v[78:79], v[86:87]
	v_pk_fma_f32 v[76:77], v[76:77], v[82:83], v[80:81]
	v_pk_fma_f32 v[74:75], v[74:75], v[84:85], v[78:79]
	v_or_b32_e32 v94, 48, v226
	v_pk_mul_f32 v[78:79], v[76:77], s[62:63] op_sel_hi:[1,0]
	v_pk_mul_f32 v[76:77], v[74:75], s[62:63] op_sel_hi:[1,0]
	v_pk_mul_f32 v[90:91], v[90:91], s[62:63] op_sel_hi:[1,0]
	v_pk_mul_f32 v[92:93], v[92:93], s[62:63] op_sel_hi:[1,0]
	v_cndmask_b32_e64 v81, v163, 0, s[8:9]
	v_cvt_pk_bf16_f32 v74, v92, v93
	v_cvt_pk_bf16_f32 v75, v90, v91
	v_cvt_pk_bf16_f32 v76, v76, v77
	v_cvt_pk_bf16_f32 v77, v78, v79
	v_mad_i64_i32 v[78:79], s[36:37], v94, s96, v[122:123]
	v_lshl_add_u64 v[78:79], v[78:79], 0, s[6:7]
	v_lshl_add_u64 v[78:79], v[78:79], 0, s[20:21]
	v_lshl_add_u64 v[78:79], v[78:79], 0, v[0:1]
	s_nop 1
	v_permlane16_swap_b32 v74, v76
	v_permlane16_swap_b32 v75, v77
	s_nop 1
	v_lshl_add_u64 v[78:79], v[78:79], 0, v[212:213]
	v_cndmask_b32_e64 v80, v162, 0, s[8:9]
	v_cndmask_b32_e64 v83, v165, 0, s[8:9]
	v_cndmask_b32_e64 v82, v164, 0, s[8:9]
	global_store_dwordx4 v[78:79], v[74:77], off
	v_pk_mul_f32 v[84:85], v[68:69], v[82:83]
	v_pk_mul_f32 v[86:87], v[66:67], v[80:81]
	v_cndmask_b32_e64 v75, v169, 1.0, s[8:9]
	v_cndmask_b32_e64 v74, v168, 1.0, s[8:9]
	v_cndmask_b32_e64 v77, v167, 1.0, s[8:9]
	v_cndmask_b32_e64 v76, v166, 1.0, s[8:9]
	v_pk_fma_f32 v[86:87], v[70:71], v[76:77], v[86:87] neg_lo:[0,0,1] neg_hi:[0,0,1]
	v_pk_fma_f32 v[84:85], v[72:73], v[74:75], v[84:85] neg_lo:[0,0,1] neg_hi:[0,0,1]
	v_pk_mul_f32 v[72:73], v[72:73], v[82:83]
	v_pk_mul_f32 v[70:71], v[70:71], v[80:81]
	v_pk_fma_f32 v[68:69], v[68:69], v[74:75], v[72:73]
	v_pk_fma_f32 v[66:67], v[66:67], v[76:77], v[70:71]
	v_pk_mul_f32 v[70:71], v[68:69], s[62:63] op_sel_hi:[1,0]
	v_pk_mul_f32 v[68:69], v[66:67], s[62:63] op_sel_hi:[1,0]
	v_pk_mul_f32 v[84:85], v[84:85], s[62:63] op_sel_hi:[1,0]
	v_pk_mul_f32 v[86:87], v[86:87], s[62:63] op_sel_hi:[1,0]
	v_cndmask_b32_e64 v73, v161, 0, s[34:35]
	v_cvt_pk_bf16_f32 v66, v86, v87
	v_cvt_pk_bf16_f32 v67, v84, v85
	v_cvt_pk_bf16_f32 v68, v68, v69
	v_cvt_pk_bf16_f32 v69, v70, v71
	v_cndmask_b32_e64 v71, v159, 0, s[34:35]
	s_nop 1
	v_permlane16_swap_b32 v66, v68
	v_permlane16_swap_b32 v67, v69
	s_nop 1
	v_cndmask_b32_e64 v70, v158, 0, s[34:35]
	v_cndmask_b32_e64 v72, v160, 0, s[34:35]
	global_store_dwordx4 v[78:79], v[66:69], off offset:256
	v_pk_mul_f32 v[74:75], v[60:61], v[72:73]
	v_pk_mul_f32 v[76:77], v[58:59], v[70:71]
	v_cndmask_b32_e64 v67, v157, 1.0, s[34:35]
	v_cndmask_b32_e64 v66, v156, 1.0, s[34:35]
	v_cndmask_b32_e64 v69, v155, 1.0, s[34:35]
	v_cndmask_b32_e64 v68, v154, 1.0, s[34:35]
	v_pk_fma_f32 v[76:77], v[62:63], v[68:69], v[76:77] neg_lo:[0,0,1] neg_hi:[0,0,1]
	v_pk_fma_f32 v[74:75], v[64:65], v[66:67], v[74:75] neg_lo:[0,0,1] neg_hi:[0,0,1]
	v_pk_mul_f32 v[64:65], v[64:65], v[72:73]
	v_pk_mul_f32 v[62:63], v[62:63], v[70:71]
	v_pk_fma_f32 v[60:61], v[60:61], v[66:67], v[64:65]
	v_pk_fma_f32 v[58:59], v[58:59], v[68:69], v[62:63]
	v_add_u32_e32 v78, 0x80, v226
	v_pk_mul_f32 v[62:63], v[60:61], s[62:63] op_sel_hi:[1,0]
	v_pk_mul_f32 v[60:61], v[58:59], s[62:63] op_sel_hi:[1,0]
	v_pk_mul_f32 v[74:75], v[74:75], s[62:63] op_sel_hi:[1,0]
	v_pk_mul_f32 v[76:77], v[76:77], s[62:63] op_sel_hi:[1,0]
	v_cndmask_b32_e64 v65, v159, 0, s[8:9]
	v_cvt_pk_bf16_f32 v58, v76, v77
	v_cvt_pk_bf16_f32 v59, v74, v75
	v_cvt_pk_bf16_f32 v60, v60, v61
	v_cvt_pk_bf16_f32 v61, v62, v63
	v_mad_i64_i32 v[62:63], s[36:37], v78, s96, v[122:123]
	v_lshl_add_u64 v[62:63], v[62:63], 0, s[6:7]
	v_lshl_add_u64 v[62:63], v[62:63], 0, s[20:21]
	v_lshl_add_u64 v[62:63], v[62:63], 0, v[0:1]
	s_nop 1
	v_permlane16_swap_b32 v58, v60
	v_permlane16_swap_b32 v59, v61
	s_nop 1
	v_lshl_add_u64 v[62:63], v[62:63], 0, v[212:213]
	v_cndmask_b32_e64 v64, v158, 0, s[8:9]
	v_cndmask_b32_e64 v67, v161, 0, s[8:9]
	v_cndmask_b32_e64 v66, v160, 0, s[8:9]
	global_store_dwordx4 v[62:63], v[58:61], off
	v_pk_mul_f32 v[68:69], v[52:53], v[66:67]
	v_pk_mul_f32 v[70:71], v[50:51], v[64:65]
	v_cndmask_b32_e64 v59, v157, 1.0, s[8:9]
	v_cndmask_b32_e64 v58, v156, 1.0, s[8:9]
	v_cndmask_b32_e64 v61, v155, 1.0, s[8:9]
	v_cndmask_b32_e64 v60, v154, 1.0, s[8:9]
	v_pk_fma_f32 v[70:71], v[54:55], v[60:61], v[70:71] neg_lo:[0,0,1] neg_hi:[0,0,1]
	v_pk_fma_f32 v[68:69], v[56:57], v[58:59], v[68:69] neg_lo:[0,0,1] neg_hi:[0,0,1]
	v_pk_mul_f32 v[56:57], v[56:57], v[66:67]
	v_pk_mul_f32 v[54:55], v[54:55], v[64:65]
	v_pk_fma_f32 v[52:53], v[52:53], v[58:59], v[56:57]
	v_pk_fma_f32 v[50:51], v[50:51], v[60:61], v[54:55]
	v_pk_mul_f32 v[54:55], v[52:53], s[62:63] op_sel_hi:[1,0]
	v_pk_mul_f32 v[52:53], v[50:51], s[62:63] op_sel_hi:[1,0]
	v_pk_mul_f32 v[68:69], v[68:69], s[62:63] op_sel_hi:[1,0]
	v_pk_mul_f32 v[70:71], v[70:71], s[62:63] op_sel_hi:[1,0]
	v_cndmask_b32_e64 v57, v149, 0, s[34:35]
	v_cvt_pk_bf16_f32 v50, v70, v71
	v_cvt_pk_bf16_f32 v51, v68, v69
	v_cvt_pk_bf16_f32 v52, v52, v53
	v_cvt_pk_bf16_f32 v53, v54, v55
	v_cndmask_b32_e64 v55, v147, 0, s[34:35]
	s_nop 1
	v_permlane16_swap_b32 v50, v52
	v_permlane16_swap_b32 v51, v53
	s_nop 1
	v_cndmask_b32_e64 v54, v146, 0, s[34:35]
	v_cndmask_b32_e64 v56, v148, 0, s[34:35]
	global_store_dwordx4 v[62:63], v[50:53], off offset:256
	v_pk_mul_f32 v[58:59], v[44:45], v[56:57]
	v_pk_mul_f32 v[60:61], v[42:43], v[54:55]
	v_cndmask_b32_e64 v51, v153, 1.0, s[34:35]
	v_cndmask_b32_e64 v50, v152, 1.0, s[34:35]
	v_cndmask_b32_e64 v53, v151, 1.0, s[34:35]
	v_cndmask_b32_e64 v52, v150, 1.0, s[34:35]
	v_pk_fma_f32 v[60:61], v[46:47], v[52:53], v[60:61] neg_lo:[0,0,1] neg_hi:[0,0,1]
	v_pk_fma_f32 v[58:59], v[48:49], v[50:51], v[58:59] neg_lo:[0,0,1] neg_hi:[0,0,1]
	v_pk_mul_f32 v[48:49], v[48:49], v[56:57]
	v_pk_mul_f32 v[46:47], v[46:47], v[54:55]
	v_pk_fma_f32 v[44:45], v[44:45], v[50:51], v[48:49]
	v_pk_fma_f32 v[42:43], v[42:43], v[52:53], v[46:47]
	v_add_u32_e32 v62, 0x90, v226
	v_pk_mul_f32 v[46:47], v[44:45], s[62:63] op_sel_hi:[1,0]
	v_pk_mul_f32 v[44:45], v[42:43], s[62:63] op_sel_hi:[1,0]
	v_pk_mul_f32 v[58:59], v[58:59], s[62:63] op_sel_hi:[1,0]
	v_pk_mul_f32 v[60:61], v[60:61], s[62:63] op_sel_hi:[1,0]
	v_cndmask_b32_e64 v49, v147, 0, s[8:9]
	v_cvt_pk_bf16_f32 v42, v60, v61
	v_cvt_pk_bf16_f32 v43, v58, v59
	v_cvt_pk_bf16_f32 v44, v44, v45
	v_cvt_pk_bf16_f32 v45, v46, v47
	v_mad_i64_i32 v[46:47], s[36:37], v62, s96, v[122:123]
	v_lshl_add_u64 v[46:47], v[46:47], 0, s[6:7]
	v_lshl_add_u64 v[46:47], v[46:47], 0, s[20:21]
	v_lshl_add_u64 v[46:47], v[46:47], 0, v[0:1]
	s_nop 1
	v_permlane16_swap_b32 v42, v44
	v_permlane16_swap_b32 v43, v45
	s_nop 1
	v_lshl_add_u64 v[46:47], v[46:47], 0, v[212:213]
	v_cndmask_b32_e64 v48, v146, 0, s[8:9]
	v_cndmask_b32_e64 v51, v149, 0, s[8:9]
	v_cndmask_b32_e64 v50, v148, 0, s[8:9]
	global_store_dwordx4 v[46:47], v[42:45], off
	v_pk_mul_f32 v[52:53], v[36:37], v[50:51]
	v_pk_mul_f32 v[54:55], v[34:35], v[48:49]
	v_cndmask_b32_e64 v43, v153, 1.0, s[8:9]
	v_cndmask_b32_e64 v42, v152, 1.0, s[8:9]
	v_cndmask_b32_e64 v45, v151, 1.0, s[8:9]
	v_cndmask_b32_e64 v44, v150, 1.0, s[8:9]
	v_pk_fma_f32 v[54:55], v[38:39], v[44:45], v[54:55] neg_lo:[0,0,1] neg_hi:[0,0,1]
	v_pk_fma_f32 v[52:53], v[40:41], v[42:43], v[52:53] neg_lo:[0,0,1] neg_hi:[0,0,1]
	v_pk_mul_f32 v[40:41], v[40:41], v[50:51]
	v_pk_mul_f32 v[38:39], v[38:39], v[48:49]
	v_pk_fma_f32 v[36:37], v[36:37], v[42:43], v[40:41]
	v_pk_fma_f32 v[34:35], v[34:35], v[44:45], v[38:39]
	v_pk_mul_f32 v[38:39], v[36:37], s[62:63] op_sel_hi:[1,0]
	v_pk_mul_f32 v[36:37], v[34:35], s[62:63] op_sel_hi:[1,0]
	v_pk_mul_f32 v[52:53], v[52:53], s[62:63] op_sel_hi:[1,0]
	v_pk_mul_f32 v[54:55], v[54:55], s[62:63] op_sel_hi:[1,0]
	v_cndmask_b32_e64 v41, v145, 0, s[34:35]
	v_cvt_pk_bf16_f32 v34, v54, v55
	v_cvt_pk_bf16_f32 v35, v52, v53
	v_cvt_pk_bf16_f32 v36, v36, v37
	v_cvt_pk_bf16_f32 v37, v38, v39
	v_cndmask_b32_e64 v39, v143, 0, s[34:35]
	s_nop 1
	v_permlane16_swap_b32 v34, v36
	v_permlane16_swap_b32 v35, v37
	s_nop 1
	v_cndmask_b32_e64 v38, v142, 0, s[34:35]
	v_cndmask_b32_e64 v40, v144, 0, s[34:35]
	global_store_dwordx4 v[46:47], v[34:37], off offset:256
	v_pk_mul_f32 v[42:43], v[28:29], v[40:41]
	v_pk_mul_f32 v[44:45], v[26:27], v[38:39]
	v_cndmask_b32_e64 v35, v141, 1.0, s[34:35]
	v_cndmask_b32_e64 v34, v140, 1.0, s[34:35]
	v_cndmask_b32_e64 v37, v139, 1.0, s[34:35]
	v_cndmask_b32_e64 v36, v138, 1.0, s[34:35]
	v_pk_fma_f32 v[44:45], v[30:31], v[36:37], v[44:45] neg_lo:[0,0,1] neg_hi:[0,0,1]
	v_pk_fma_f32 v[42:43], v[32:33], v[34:35], v[42:43] neg_lo:[0,0,1] neg_hi:[0,0,1]
	v_pk_mul_f32 v[32:33], v[32:33], v[40:41]
	v_pk_mul_f32 v[30:31], v[30:31], v[38:39]
	v_pk_fma_f32 v[28:29], v[28:29], v[34:35], v[32:33]
	v_pk_fma_f32 v[26:27], v[26:27], v[36:37], v[30:31]
	v_add_u32_e32 v46, 0xa0, v226
	v_pk_mul_f32 v[30:31], v[28:29], s[62:63] op_sel_hi:[1,0]
	v_pk_mul_f32 v[28:29], v[26:27], s[62:63] op_sel_hi:[1,0]
	v_pk_mul_f32 v[42:43], v[42:43], s[62:63] op_sel_hi:[1,0]
	v_pk_mul_f32 v[44:45], v[44:45], s[62:63] op_sel_hi:[1,0]
	v_cndmask_b32_e64 v33, v143, 0, s[8:9]
	v_cvt_pk_bf16_f32 v26, v44, v45
	v_cvt_pk_bf16_f32 v27, v42, v43
	v_cvt_pk_bf16_f32 v28, v28, v29
	v_cvt_pk_bf16_f32 v29, v30, v31
	v_mad_i64_i32 v[30:31], s[36:37], v46, s96, v[122:123]
	v_lshl_add_u64 v[30:31], v[30:31], 0, s[6:7]
	v_lshl_add_u64 v[30:31], v[30:31], 0, s[20:21]
	v_lshl_add_u64 v[30:31], v[30:31], 0, v[0:1]
	s_nop 1
	v_permlane16_swap_b32 v26, v28
	v_permlane16_swap_b32 v27, v29
	s_nop 1
	v_lshl_add_u64 v[30:31], v[30:31], 0, v[212:213]
	v_cndmask_b32_e64 v32, v142, 0, s[8:9]
	v_cndmask_b32_e64 v35, v145, 0, s[8:9]
	v_cndmask_b32_e64 v34, v144, 0, s[8:9]
	global_store_dwordx4 v[30:31], v[26:29], off
	v_pk_mul_f32 v[36:37], v[20:21], v[34:35]
	v_pk_mul_f32 v[38:39], v[18:19], v[32:33]
	v_cndmask_b32_e64 v27, v141, 1.0, s[8:9]
	v_cndmask_b32_e64 v26, v140, 1.0, s[8:9]
	v_cndmask_b32_e64 v29, v139, 1.0, s[8:9]
	v_cndmask_b32_e64 v28, v138, 1.0, s[8:9]
	v_pk_fma_f32 v[38:39], v[22:23], v[28:29], v[38:39] neg_lo:[0,0,1] neg_hi:[0,0,1]
	v_pk_fma_f32 v[36:37], v[24:25], v[26:27], v[36:37] neg_lo:[0,0,1] neg_hi:[0,0,1]
	v_pk_mul_f32 v[24:25], v[24:25], v[34:35]
	v_pk_mul_f32 v[22:23], v[22:23], v[32:33]
	v_pk_fma_f32 v[20:21], v[20:21], v[26:27], v[24:25]
	v_pk_fma_f32 v[18:19], v[18:19], v[28:29], v[22:23]
	v_pk_mul_f32 v[22:23], v[20:21], s[62:63] op_sel_hi:[1,0]
	v_pk_mul_f32 v[20:21], v[18:19], s[62:63] op_sel_hi:[1,0]
	v_pk_mul_f32 v[36:37], v[36:37], s[62:63] op_sel_hi:[1,0]
	v_pk_mul_f32 v[38:39], v[38:39], s[62:63] op_sel_hi:[1,0]
	v_cndmask_b32_e64 v25, v133, 0, s[34:35]
	v_cvt_pk_bf16_f32 v18, v38, v39
	v_cvt_pk_bf16_f32 v19, v36, v37
	v_cvt_pk_bf16_f32 v20, v20, v21
	v_cvt_pk_bf16_f32 v21, v22, v23
	v_cndmask_b32_e64 v23, v131, 0, s[34:35]
	s_nop 1
	v_permlane16_swap_b32 v18, v20
	v_permlane16_swap_b32 v19, v21
	s_nop 1
	v_cndmask_b32_e64 v22, v130, 0, s[34:35]
	v_cndmask_b32_e64 v24, v132, 0, s[34:35]
	global_store_dwordx4 v[30:31], v[18:21], off offset:256
	v_pk_mul_f32 v[26:27], v[12:13], v[24:25]
	v_pk_mul_f32 v[28:29], v[10:11], v[22:23]
	v_cndmask_b32_e64 v19, v137, 1.0, s[34:35]
	v_cndmask_b32_e64 v18, v136, 1.0, s[34:35]
	v_cndmask_b32_e64 v21, v135, 1.0, s[34:35]
	v_cndmask_b32_e64 v20, v134, 1.0, s[34:35]
	v_pk_fma_f32 v[28:29], v[14:15], v[20:21], v[28:29] neg_lo:[0,0,1] neg_hi:[0,0,1]
	v_pk_fma_f32 v[26:27], v[16:17], v[18:19], v[26:27] neg_lo:[0,0,1] neg_hi:[0,0,1]
	v_pk_mul_f32 v[16:17], v[16:17], v[24:25]
	v_pk_mul_f32 v[14:15], v[14:15], v[22:23]
	v_pk_fma_f32 v[12:13], v[12:13], v[18:19], v[16:17]
	v_pk_fma_f32 v[10:11], v[10:11], v[20:21], v[14:15]
	v_add_u32_e32 v30, 0xb0, v226
	v_pk_mul_f32 v[14:15], v[12:13], s[62:63] op_sel_hi:[1,0]
	v_pk_mul_f32 v[12:13], v[10:11], s[62:63] op_sel_hi:[1,0]
	v_pk_mul_f32 v[26:27], v[26:27], s[62:63] op_sel_hi:[1,0]
	v_pk_mul_f32 v[28:29], v[28:29], s[62:63] op_sel_hi:[1,0]
	v_cndmask_b32_e64 v17, v133, 0, s[8:9]
	v_cvt_pk_bf16_f32 v10, v28, v29
	v_cvt_pk_bf16_f32 v11, v26, v27
	v_cvt_pk_bf16_f32 v12, v12, v13
	v_cvt_pk_bf16_f32 v13, v14, v15
	v_mad_i64_i32 v[14:15], s[34:35], v30, s96, v[122:123]
	v_lshl_add_u64 v[14:15], v[14:15], 0, s[6:7]
	v_lshl_add_u64 v[14:15], v[14:15], 0, s[20:21]
	v_lshl_add_u64 v[14:15], v[14:15], 0, v[0:1]
	s_nop 1
	v_permlane16_swap_b32 v10, v12
	v_permlane16_swap_b32 v11, v13
	s_nop 1
	v_lshl_add_u64 v[138:139], v[14:15], 0, v[212:213]
	v_cndmask_b32_e64 v15, v131, 0, s[8:9]
	v_cndmask_b32_e64 v14, v130, 0, s[8:9]
	v_cndmask_b32_e64 v16, v132, 0, s[8:9]
	global_store_dwordx4 v[138:139], v[10:13], off
	v_pk_mul_f32 v[18:19], v[4:5], v[16:17]
	v_pk_mul_f32 v[20:21], v[2:3], v[14:15]
	v_cndmask_b32_e64 v11, v137, 1.0, s[8:9]
	v_cndmask_b32_e64 v10, v136, 1.0, s[8:9]
	v_cndmask_b32_e64 v13, v135, 1.0, s[8:9]
	v_cndmask_b32_e64 v12, v134, 1.0, s[8:9]
	v_pk_fma_f32 v[20:21], v[6:7], v[12:13], v[20:21] neg_lo:[0,0,1] neg_hi:[0,0,1]
	v_pk_fma_f32 v[18:19], v[8:9], v[10:11], v[18:19] neg_lo:[0,0,1] neg_hi:[0,0,1]
	v_pk_mul_f32 v[8:9], v[8:9], v[16:17]
	v_pk_mul_f32 v[6:7], v[6:7], v[14:15]
	v_pk_fma_f32 v[4:5], v[4:5], v[10:11], v[8:9]
	v_pk_fma_f32 v[2:3], v[2:3], v[12:13], v[6:7]
	v_pk_mul_f32 v[18:19], v[18:19], s[62:63] op_sel_hi:[1,0]
	v_pk_mul_f32 v[20:21], v[20:21], s[62:63] op_sel_hi:[1,0]
	v_pk_mul_f32 v[4:5], v[4:5], s[62:63] op_sel_hi:[1,0]
	v_pk_mul_f32 v[2:3], v[2:3], s[62:63] op_sel_hi:[1,0]
	v_cvt_pk_bf16_f32 v130, v20, v21
	v_cvt_pk_bf16_f32 v131, v18, v19
	s_nop 0
	v_cvt_pk_bf16_f32 v132, v2, v3
	v_cvt_pk_bf16_f32 v133, v4, v5
	s_nop 0
	s_nop 1
	v_permlane16_swap_b32 v130, v132
	v_permlane16_swap_b32 v131, v133
	s_nop 1
	s_andn2_b64 vcc, exec, s[22:23]
	s_mov_b64 s[6:7], -1
	global_store_dwordx4 v[138:139], v[130:133], off offset:256
	s_cbranch_vccnz .LBB0_423
.LBB0_454:
	s_branch .LBB0_422
.LBB0_456:
	s_waitcnt vmcnt(0)
	s_barrier

.LBB0_604:
	s_ashr_i32 s35, s34, 31
	s_lshl_b64 s[36:37], s[34:35], 20
	s_add_u32 s36, s73, s36
	s_addc_u32 s37, s89, s37
	s_and_b64 s[38:39], s[6:7], exec
	s_cselect_b32 s11, s37, s81
	s_cselect_b32 s35, s36, s80
	s_ashr_i32 s31, s30, 31
	s_lshl_b64 s[38:39], s[30:31], 20
	s_add_u32 s38, s97, s38
	s_addc_u32 s39, s65, s39
	s_and_b64 s[82:83], s[6:7], exec
	s_cselect_b32 s31, s39, s9
	s_cselect_b32 s79, s38, s8
	s_add_u32 s84, s8, 0x100
	s_addc_u32 s85, s9, 0
	s_add_u32 s8, s80, 0x80080
	s_addc_u32 s9, s81, 0
	s_mov_b32 s86, -2
	s_cmp_eq_u32 s99, 0
	s_cbranch_scc1 .Lno_e2_G1
	s_and_b64 s[100:101], exec, s[16:17]
	s_cbranch_scc0 .Lno_e2_G1
	s_barrier
.Lno_e2_G1:
.Lpeel_G1:
	s_add_u32 s80, s8, 0xfff80080
	s_addc_u32 s81, s9, -1
	s_add_i32 s87, 0, 0x10000
	s_cmp_eq_u32 s86, 28
	s_cselect_b32 s83, s11, s81
	s_cselect_b32 s82, s35, s80
	s_cselect_b32 s81, s31, s85
	s_cselect_b32 s80, s79, s84
	s_add_i32 s92, 0, 0x14000
	v_add_u32_e32 v142, s87, v228
	v_add_u32_e32 v158, s92, v228
	ds_read_b128 v[126:129], v142
	ds_read_b128 v[134:137], v142 offset:1024
	ds_read_b128 v[138:141], v142 offset:2048
	ds_read_b128 v[142:145], v142 offset:3072
	ds_read_b128 v[146:149], v158
	ds_read_b128 v[150:153], v158 offset:1024
	ds_read_b128 v[154:157], v158 offset:2048
	ds_read_b128 v[158:161], v158 offset:3072
	v_lshl_add_u64 v[202:203], s[8:9], 0, v[210:211]
	s_add_i32 m0, s61, 0xc000
	ds_read_b128 v[162:165], v233
	ds_read_b128 v[166:169], v233 offset:1024
	ds_read_b128 v[170:173], v233 offset:2048
	ds_read_b128 v[174:177], v233 offset:3072
	ds_read_b128 v[178:181], v233 offset:4096
	ds_read_b128 v[182:185], v233 offset:5120
	ds_read_b128 v[186:189], v233 offset:6144
	ds_read_b128 v[190:193], v233 offset:7168
	global_load_lds_dwordx4 v[202:203], off
	v_lshl_add_u64 v[202:203], s[8:9], 0, v[208:209]
	s_add_i32 m0, s61, 0xe000
	s_nop 0
	global_load_lds_dwordx4 v[202:203], off
	s_waitcnt vmcnt(8)
	s_waitcnt lgkmcnt(0)
	s_barrier
	s_setprio 1
	s_waitcnt lgkmcnt(0)
	v_mfma_f32_16x16x32_bf16 v[130:133], v[126:129], v[162:165], 0
	v_mfma_f32_16x16x32_bf16 v[122:125], v[138:141], v[162:165], 0
	v_mfma_f32_16x16x32_bf16 v[110:113], v[126:129], v[170:173], 0
	v_mfma_f32_16x16x32_bf16 v[106:109], v[138:141], v[170:173], 0
	v_mfma_f32_16x16x32_bf16 v[94:97], v[126:129], v[178:181], 0
	v_mfma_f32_16x16x32_bf16 v[90:93], v[138:141], v[178:181], 0
	v_mfma_f32_16x16x32_bf16 v[78:81], v[126:129], v[186:189], 0
	v_mfma_f32_16x16x32_bf16 v[74:77], v[138:141], v[186:189], 0
	v_mfma_f32_16x16x32_bf16 v[130:133], v[134:137], v[166:169], v[130:133]
	v_mfma_f32_16x16x32_bf16 v[122:125], v[142:145], v[166:169], v[122:125]
	v_mfma_f32_16x16x32_bf16 v[110:113], v[134:137], v[174:177], v[110:113]
	v_mfma_f32_16x16x32_bf16 v[106:109], v[142:145], v[174:177], v[106:109]
	v_mfma_f32_16x16x32_bf16 v[94:97], v[134:137], v[182:185], v[94:97]
	v_mfma_f32_16x16x32_bf16 v[90:93], v[142:145], v[182:185], v[90:93]
	v_mfma_f32_16x16x32_bf16 v[78:81], v[134:137], v[190:193], v[78:81]
	v_mfma_f32_16x16x32_bf16 v[74:77], v[142:145], v[190:193], v[74:77]
	s_setprio 0
	s_setprio 1
	v_mfma_f32_16x16x32_bf16 v[118:121], v[146:149], v[162:165], 0
	v_mfma_f32_16x16x32_bf16 v[114:117], v[154:157], v[162:165], 0
	v_mfma_f32_16x16x32_bf16 v[102:105], v[146:149], v[170:173], 0
	v_mfma_f32_16x16x32_bf16 v[98:101], v[154:157], v[170:173], 0
	v_mfma_f32_16x16x32_bf16 v[86:89], v[146:149], v[178:181], 0
	v_mfma_f32_16x16x32_bf16 v[82:85], v[154:157], v[178:181], 0
	v_mfma_f32_16x16x32_bf16 v[70:73], v[146:149], v[186:189], 0
	v_mfma_f32_16x16x32_bf16 v[66:69], v[154:157], v[186:189], 0
	v_mfma_f32_16x16x32_bf16 v[118:121], v[150:153], v[166:169], v[118:121]
	v_mfma_f32_16x16x32_bf16 v[114:117], v[158:161], v[166:169], v[114:117]
	v_mfma_f32_16x16x32_bf16 v[102:105], v[150:153], v[174:177], v[102:105]
	v_mfma_f32_16x16x32_bf16 v[98:101], v[158:161], v[174:177], v[98:101]
	v_mfma_f32_16x16x32_bf16 v[86:89], v[150:153], v[182:185], v[86:89]
	v_mfma_f32_16x16x32_bf16 v[82:85], v[158:161], v[182:185], v[82:85]
	v_mfma_f32_16x16x32_bf16 v[70:73], v[150:153], v[190:193], v[70:73]
	v_mfma_f32_16x16x32_bf16 v[66:69], v[158:161], v[190:193], v[66:69]
	s_setprio 0
	s_barrier
	s_add_i32 s87, s87, s95
	v_lshl_add_u64 v[202:203], s[80:81], 0, v[194:195]
	s_mov_b32 m0, s87
	ds_read_b128 v[162:165], v233 offset:16384
	ds_read_b128 v[166:169], v233 offset:17408
	ds_read_b128 v[170:173], v233 offset:18432
	ds_read_b128 v[174:177], v233 offset:19456
	ds_read_b128 v[178:181], v233 offset:20480
	ds_read_b128 v[182:185], v233 offset:21504
	ds_read_b128 v[186:189], v233 offset:22528
	ds_read_b128 v[190:193], v233 offset:23552
	global_load_lds_dwordx4 v[202:203], off
	s_add_i32 m0, s87, 0x2000
	s_add_u32 vcc_lo, s80, 0x80000
	v_lshl_add_u64 v[204:205], s[80:81], 0, v[196:197]
	s_addc_u32 vcc_hi, s81, 0
	s_add_i32 s87, s92, s95
	global_load_lds_dwordx4 v[204:205], off
	v_lshl_add_u64 v[206:207], vcc, 0, v[194:195]
	s_mov_b32 m0, s87
	v_lshl_add_u64 v[214:215], s[82:83], 0, v[196:197]
	global_load_lds_dwordx4 v[206:207], off
	v_lshl_add_u64 v[206:207], vcc, 0, v[196:197]
	s_add_i32 m0, s87, 0x2000
	s_nop 0
	global_load_lds_dwordx4 v[206:207], off
	v_lshl_add_u64 v[206:207], s[82:83], 0, v[194:195]
	s_mov_b32 m0, s61
	s_nop 0
	global_load_lds_dwordx4 v[206:207], off
	s_mov_b32 m0, s44
	s_nop 0
	global_load_lds_dwordx4 v[214:215], off
	s_waitcnt vmcnt(8)
	s_waitcnt lgkmcnt(0)
	s_barrier
	s_setprio 1
	s_waitcnt lgkmcnt(0)
	v_mfma_f32_16x16x32_bf16 v[62:65], v[126:129], v[162:165], 0
	v_mfma_f32_16x16x32_bf16 v[58:61], v[138:141], v[162:165], 0
	v_mfma_f32_16x16x32_bf16 v[46:49], v[126:129], v[170:173], 0
	v_mfma_f32_16x16x32_bf16 v[42:45], v[138:141], v[170:173], 0
	v_mfma_f32_16x16x32_bf16 v[30:33], v[126:129], v[178:181], 0
	v_mfma_f32_16x16x32_bf16 v[26:29], v[138:141], v[178:181], 0
	v_mfma_f32_16x16x32_bf16 v[14:17], v[126:129], v[186:189], 0
	v_mfma_f32_16x16x32_bf16 v[10:13], v[138:141], v[186:189], 0
	v_mfma_f32_16x16x32_bf16 v[62:65], v[134:137], v[166:169], v[62:65]
	v_mfma_f32_16x16x32_bf16 v[58:61], v[142:145], v[166:169], v[58:61]
	v_mfma_f32_16x16x32_bf16 v[46:49], v[134:137], v[174:177], v[46:49]
	v_mfma_f32_16x16x32_bf16 v[42:45], v[142:145], v[174:177], v[42:45]
	v_mfma_f32_16x16x32_bf16 v[30:33], v[134:137], v[182:185], v[30:33]
	v_mfma_f32_16x16x32_bf16 v[26:29], v[142:145], v[182:185], v[26:29]
	v_mfma_f32_16x16x32_bf16 v[14:17], v[134:137], v[190:193], v[14:17]
	v_mfma_f32_16x16x32_bf16 v[10:13], v[142:145], v[190:193], v[10:13]
	s_setprio 0
	s_setprio 1
	v_mfma_f32_16x16x32_bf16 v[54:57], v[146:149], v[162:165], 0
	v_mfma_f32_16x16x32_bf16 v[50:53], v[154:157], v[162:165], 0
	v_mfma_f32_16x16x32_bf16 v[38:41], v[146:149], v[170:173], 0
	v_mfma_f32_16x16x32_bf16 v[34:37], v[154:157], v[170:173], 0
	v_mfma_f32_16x16x32_bf16 v[22:25], v[146:149], v[178:181], 0
	v_mfma_f32_16x16x32_bf16 v[18:21], v[154:157], v[178:181], 0
	v_mfma_f32_16x16x32_bf16 v[6:9], v[146:149], v[186:189], 0
	v_mfma_f32_16x16x32_bf16 v[2:5], v[154:157], v[186:189], 0
	v_mfma_f32_16x16x32_bf16 v[54:57], v[150:153], v[166:169], v[54:57]
	v_mfma_f32_16x16x32_bf16 v[50:53], v[158:161], v[166:169], v[50:53]
	v_mfma_f32_16x16x32_bf16 v[38:41], v[150:153], v[174:177], v[38:41]
	v_mfma_f32_16x16x32_bf16 v[34:37], v[158:161], v[174:177], v[34:37]
	v_mfma_f32_16x16x32_bf16 v[22:25], v[150:153], v[182:185], v[22:25]
	v_mfma_f32_16x16x32_bf16 v[18:21], v[158:161], v[182:185], v[18:21]
	v_mfma_f32_16x16x32_bf16 v[6:9], v[150:153], v[190:193], v[6:9]
	v_mfma_f32_16x16x32_bf16 v[2:5], v[158:161], v[190:193], v[2:5]
	s_setprio 0
	s_barrier
	s_add_i32 s87, 0, 0x18000
	s_add_i32 s92, 0, 0x1c000
	v_add_u32_e32 v142, s87, v228
	v_add_u32_e32 v158, s92, v228
	ds_read_b128 v[126:129], v142
	ds_read_b128 v[134:137], v142 offset:1024
	ds_read_b128 v[138:141], v142 offset:2048
	ds_read_b128 v[142:145], v142 offset:3072
	ds_read_b128 v[146:149], v158
	ds_read_b128 v[150:153], v158 offset:1024
	ds_read_b128 v[154:157], v158 offset:2048
	ds_read_b128 v[158:161], v158 offset:3072
	s_add_u32 s82, s82, 0x80000
	s_addc_u32 s83, s83, 0
	s_mov_b32 m0, s45
	v_lshl_add_u64 v[216:217], s[82:83], 0, v[194:195]
	ds_read_b128 v[162:165], v233 offset:32768
	ds_read_b128 v[166:169], v233 offset:33792
	ds_read_b128 v[170:173], v233 offset:34816
	ds_read_b128 v[174:177], v233 offset:35840
	ds_read_b128 v[178:181], v233 offset:36864
	ds_read_b128 v[182:185], v233 offset:37888
	ds_read_b128 v[186:189], v233 offset:38912
	ds_read_b128 v[190:193], v233 offset:39936
	global_load_lds_dwordx4 v[216:217], off
	v_lshl_add_u64 v[216:217], s[82:83], 0, v[196:197]
	s_mov_b32 m0, s88
	s_nop 0
	global_load_lds_dwordx4 v[216:217], off
	s_waitcnt vmcnt(8)
	s_waitcnt lgkmcnt(0)
	s_barrier
	s_setprio 1
	s_waitcnt lgkmcnt(0)
	v_mfma_f32_16x16x32_bf16 v[130:133], v[126:129], v[162:165], v[130:133]
	v_mfma_f32_16x16x32_bf16 v[122:125], v[138:141], v[162:165], v[122:125]
	v_mfma_f32_16x16x32_bf16 v[110:113], v[126:129], v[170:173], v[110:113]
	v_mfma_f32_16x16x32_bf16 v[106:109], v[138:141], v[170:173], v[106:109]
	v_mfma_f32_16x16x32_bf16 v[94:97], v[126:129], v[178:181], v[94:97]
	v_mfma_f32_16x16x32_bf16 v[90:93], v[138:141], v[178:181], v[90:93]
	v_mfma_f32_16x16x32_bf16 v[78:81], v[126:129], v[186:189], v[78:81]
	v_mfma_f32_16x16x32_bf16 v[74:77], v[138:141], v[186:189], v[74:77]
	v_mfma_f32_16x16x32_bf16 v[130:133], v[134:137], v[166:169], v[130:133]
	v_mfma_f32_16x16x32_bf16 v[122:125], v[142:145], v[166:169], v[122:125]
	v_mfma_f32_16x16x32_bf16 v[110:113], v[134:137], v[174:177], v[110:113]
	v_mfma_f32_16x16x32_bf16 v[106:109], v[142:145], v[174:177], v[106:109]
	v_mfma_f32_16x16x32_bf16 v[94:97], v[134:137], v[182:185], v[94:97]
	v_mfma_f32_16x16x32_bf16 v[90:93], v[142:145], v[182:185], v[90:93]
	v_mfma_f32_16x16x32_bf16 v[78:81], v[134:137], v[190:193], v[78:81]
	v_mfma_f32_16x16x32_bf16 v[74:77], v[142:145], v[190:193], v[74:77]
	s_setprio 0
	s_setprio 1
	v_mfma_f32_16x16x32_bf16 v[118:121], v[146:149], v[162:165], v[118:121]
	v_mfma_f32_16x16x32_bf16 v[114:117], v[154:157], v[162:165], v[114:117]
	v_mfma_f32_16x16x32_bf16 v[102:105], v[146:149], v[170:173], v[102:105]
	v_mfma_f32_16x16x32_bf16 v[98:101], v[154:157], v[170:173], v[98:101]
	v_mfma_f32_16x16x32_bf16 v[86:89], v[146:149], v[178:181], v[86:89]
	v_mfma_f32_16x16x32_bf16 v[82:85], v[154:157], v[178:181], v[82:85]
	v_mfma_f32_16x16x32_bf16 v[70:73], v[146:149], v[186:189], v[70:73]
	v_mfma_f32_16x16x32_bf16 v[66:69], v[154:157], v[186:189], v[66:69]
	v_mfma_f32_16x16x32_bf16 v[118:121], v[150:153], v[166:169], v[118:121]
	v_mfma_f32_16x16x32_bf16 v[114:117], v[158:161], v[166:169], v[114:117]
	v_mfma_f32_16x16x32_bf16 v[102:105], v[150:153], v[174:177], v[102:105]
	v_mfma_f32_16x16x32_bf16 v[98:101], v[158:161], v[174:177], v[98:101]
	v_mfma_f32_16x16x32_bf16 v[86:89], v[150:153], v[182:185], v[86:89]
	v_mfma_f32_16x16x32_bf16 v[82:85], v[158:161], v[182:185], v[82:85]
	v_mfma_f32_16x16x32_bf16 v[70:73], v[150:153], v[190:193], v[70:73]
	v_mfma_f32_16x16x32_bf16 v[66:69], v[158:161], v[190:193], v[66:69]
	s_setprio 0
	s_barrier
	s_add_i32 s82, s87, s95
	v_lshl_add_u64 v[202:203], v[202:203], 0, s[54:55]
	s_mov_b32 m0, s82
	ds_read_b128 v[162:165], v233 offset:49152
	ds_read_b128 v[166:169], v233 offset:50176
	ds_read_b128 v[170:173], v233 offset:51200
	ds_read_b128 v[174:177], v233 offset:52224
	ds_read_b128 v[178:181], v233 offset:53248
	ds_read_b128 v[182:185], v233 offset:54272
	ds_read_b128 v[186:189], v233 offset:55296
	ds_read_b128 v[190:193], v233 offset:56320
	global_load_lds_dwordx4 v[202:203], off
	s_add_i32 m0, s82, 0x2000
	s_add_u32 s80, s80, 0x80080
	v_lshl_add_u64 v[202:203], v[204:205], 0, s[54:55]
	s_addc_u32 s81, s81, 0
	s_add_i32 s82, s92, s95
	global_load_lds_dwordx4 v[202:203], off
	v_lshl_add_u64 v[202:203], s[80:81], 0, v[194:195]
	s_mov_b32 m0, s82
	s_nop 0
	global_load_lds_dwordx4 v[202:203], off
	v_lshl_add_u64 v[202:203], s[80:81], 0, v[196:197]
	s_add_i32 m0, s82, 0x2000
	s_nop 0
	global_load_lds_dwordx4 v[202:203], off
	v_lshl_add_u64 v[202:203], v[206:207], 0, s[54:55]
	s_mov_b32 m0, s48
	s_nop 0
	global_load_lds_dwordx4 v[202:203], off
	v_lshl_add_u64 v[202:203], v[214:215], 0, s[54:55]
	s_mov_b32 m0, s49
	s_nop 0
	global_load_lds_dwordx4 v[202:203], off
	s_waitcnt vmcnt(8)
	s_waitcnt lgkmcnt(0)
	s_barrier
	s_setprio 1
	s_waitcnt lgkmcnt(0)
	v_mfma_f32_16x16x32_bf16 v[62:65], v[126:129], v[162:165], v[62:65]
	v_mfma_f32_16x16x32_bf16 v[58:61], v[138:141], v[162:165], v[58:61]
	v_mfma_f32_16x16x32_bf16 v[46:49], v[126:129], v[170:173], v[46:49]
	v_mfma_f32_16x16x32_bf16 v[42:45], v[138:141], v[170:173], v[42:45]
	v_mfma_f32_16x16x32_bf16 v[30:33], v[126:129], v[178:181], v[30:33]
	v_mfma_f32_16x16x32_bf16 v[26:29], v[138:141], v[178:181], v[26:29]
	v_mfma_f32_16x16x32_bf16 v[14:17], v[126:129], v[186:189], v[14:17]
	v_mfma_f32_16x16x32_bf16 v[10:13], v[138:141], v[186:189], v[10:13]
	v_mfma_f32_16x16x32_bf16 v[62:65], v[134:137], v[166:169], v[62:65]
	v_mfma_f32_16x16x32_bf16 v[58:61], v[142:145], v[166:169], v[58:61]
	v_mfma_f32_16x16x32_bf16 v[46:49], v[134:137], v[174:177], v[46:49]
	v_mfma_f32_16x16x32_bf16 v[42:45], v[142:145], v[174:177], v[42:45]
	v_mfma_f32_16x16x32_bf16 v[30:33], v[134:137], v[182:185], v[30:33]
	v_mfma_f32_16x16x32_bf16 v[26:29], v[142:145], v[182:185], v[26:29]
	v_mfma_f32_16x16x32_bf16 v[14:17], v[134:137], v[190:193], v[14:17]
	v_mfma_f32_16x16x32_bf16 v[10:13], v[142:145], v[190:193], v[10:13]
	s_setprio 0
	s_setprio 1
	v_mfma_f32_16x16x32_bf16 v[54:57], v[146:149], v[162:165], v[54:57]
	v_mfma_f32_16x16x32_bf16 v[50:53], v[154:157], v[162:165], v[50:53]
	v_mfma_f32_16x16x32_bf16 v[38:41], v[146:149], v[170:173], v[38:41]
	v_mfma_f32_16x16x32_bf16 v[34:37], v[154:157], v[170:173], v[34:37]
	v_mfma_f32_16x16x32_bf16 v[22:25], v[146:149], v[178:181], v[22:25]
	v_mfma_f32_16x16x32_bf16 v[18:21], v[154:157], v[178:181], v[18:21]
	v_mfma_f32_16x16x32_bf16 v[6:9], v[146:149], v[186:189], v[6:9]
	v_mfma_f32_16x16x32_bf16 v[2:5], v[154:157], v[186:189], v[2:5]
	v_mfma_f32_16x16x32_bf16 v[54:57], v[150:153], v[166:169], v[54:57]
	v_mfma_f32_16x16x32_bf16 v[50:53], v[158:161], v[166:169], v[50:53]
	v_mfma_f32_16x16x32_bf16 v[38:41], v[150:153], v[174:177], v[38:41]
	v_mfma_f32_16x16x32_bf16 v[34:37], v[158:161], v[174:177], v[34:37]
	v_mfma_f32_16x16x32_bf16 v[22:25], v[150:153], v[182:185], v[22:25]
	v_mfma_f32_16x16x32_bf16 v[18:21], v[158:161], v[182:185], v[18:21]
	v_mfma_f32_16x16x32_bf16 v[6:9], v[150:153], v[190:193], v[6:9]
	v_mfma_f32_16x16x32_bf16 v[2:5], v[158:161], v[190:193], v[2:5]
	s_setprio 0
	s_barrier
	s_add_i32 s86, s86, 2
	s_add_u32 s84, s84, 0x100
	s_addc_u32 s85, s85, 0
	s_add_u32 s8, s8, 0x100
	s_addc_u32 s9, s9, 0
	s_cmp_gt_u32 s86, 29
	s_cbranch_scc1 .Lpeel_exit_G1

.LBB0_663:
	s_andn2_b64 vcc, exec, s[6:7]
	s_mov_b64 s[6:7], -1
	s_cbranch_vccnz .LBB0_601
	s_branch .LBB0_600

.LBB0_1059:
	s_ashr_i32 s19, s18, 31
	s_lshl_b64 s[20:21], s[18:19], 20
	s_add_u32 s20, s67, s20
	s_addc_u32 s21, s78, s21
	s_and_b64 s[22:23], s[4:5], exec
	s_cselect_b32 s19, s21, s29
	s_cselect_b32 s33, s20, s28
	s_ashr_i32 s17, s16, 31
	s_lshl_b64 s[22:23], s[16:17], 20
	s_add_u32 s22, s79, s22
	s_addc_u32 s23, s80, s23
	s_and_b64 s[30:31], s[4:5], exec
	s_cselect_b32 s17, s23, s27
	s_cselect_b32 s44, s22, s26
	s_add_u32 s45, s26, 0x100
	s_addc_u32 s48, s27, 0
	s_add_u32 s26, s28, 0x80080
	s_addc_u32 s27, s29, 0
	s_mov_b32 s49, -2
	s_cmp_eq_u32 s99, 0
	s_cbranch_scc1 .Lno_e2_G3
	s_and_b64 s[100:101], exec, s[8:9]
	s_cbranch_scc0 .Lno_e2_G3
	s_barrier
.Lno_e2_G3:
.Lpeel_G3:
	s_add_u32 s28, s26, 0xfff80080
	s_addc_u32 s29, s27, -1
	s_add_i32 s61, 0, 0x10000
	s_cmp_eq_u32 s49, 28
	s_cselect_b32 s31, s19, s29
	s_cselect_b32 s30, s33, s28
	v_add_u32_e32 v141, s61, v138
	s_cselect_b32 s29, s17, s48
	s_cselect_b32 s28, s44, s45
	s_add_i32 s73, 0, 0x14000
	ds_read_b128 v[142:145], v141
	ds_read_b128 v[146:149], v141 offset:1024
	ds_read_b128 v[150:153], v141 offset:2048
	ds_read_b128 v[154:157], v141 offset:3072
	v_add_u32_e32 v141, s73, v138
	ds_read_b128 v[158:161], v141
	ds_read_b128 v[162:165], v141 offset:1024
	ds_read_b128 v[166:169], v141 offset:2048
	ds_read_b128 v[170:173], v141 offset:3072
	v_lshl_add_u64 v[206:207], s[26:27], 0, v[134:135]
	s_add_i32 m0, s82, 0xc000
	ds_read_b128 v[174:177], v140
	ds_read_b128 v[178:181], v140 offset:1024
	ds_read_b128 v[182:185], v140 offset:2048
	ds_read_b128 v[186:189], v140 offset:3072
	ds_read_b128 v[190:193], v140 offset:4096
	ds_read_b128 v[194:197], v140 offset:5120
	ds_read_b128 v[198:201], v140 offset:6144
	ds_read_b128 v[202:205], v140 offset:7168
	global_load_lds_dwordx4 v[206:207], off
	v_lshl_add_u64 v[206:207], s[26:27], 0, v[132:133]
	s_add_i32 m0, s82, 0xe000
	s_nop 0
	global_load_lds_dwordx4 v[206:207], off
	s_waitcnt vmcnt(8)
	s_waitcnt lgkmcnt(0)
	s_barrier
	s_setprio 1
	s_waitcnt lgkmcnt(0)
	v_mfma_f32_16x16x32_bf16 v[126:129], v[142:145], v[174:177], 0
	v_mfma_f32_16x16x32_bf16 v[118:121], v[150:153], v[174:177], 0
	v_mfma_f32_16x16x32_bf16 v[110:113], v[142:145], v[182:185], 0
	v_mfma_f32_16x16x32_bf16 v[102:105], v[150:153], v[182:185], 0
	v_mfma_f32_16x16x32_bf16 v[94:97], v[142:145], v[190:193], 0
	v_mfma_f32_16x16x32_bf16 v[86:89], v[150:153], v[190:193], 0
	v_mfma_f32_16x16x32_bf16 v[78:81], v[142:145], v[198:201], 0
	v_mfma_f32_16x16x32_bf16 v[70:73], v[150:153], v[198:201], 0
	v_mfma_f32_16x16x32_bf16 v[126:129], v[146:149], v[178:181], v[126:129]
	v_mfma_f32_16x16x32_bf16 v[118:121], v[154:157], v[178:181], v[118:121]
	v_mfma_f32_16x16x32_bf16 v[110:113], v[146:149], v[186:189], v[110:113]
	v_mfma_f32_16x16x32_bf16 v[102:105], v[154:157], v[186:189], v[102:105]
	v_mfma_f32_16x16x32_bf16 v[94:97], v[146:149], v[194:197], v[94:97]
	v_mfma_f32_16x16x32_bf16 v[86:89], v[154:157], v[194:197], v[86:89]
	v_mfma_f32_16x16x32_bf16 v[78:81], v[146:149], v[202:205], v[78:81]
	v_mfma_f32_16x16x32_bf16 v[70:73], v[154:157], v[202:205], v[70:73]
	s_setprio 0
	s_setprio 1
	v_mfma_f32_16x16x32_bf16 v[122:125], v[158:161], v[174:177], 0
	v_mfma_f32_16x16x32_bf16 v[114:117], v[166:169], v[174:177], 0
	v_mfma_f32_16x16x32_bf16 v[106:109], v[158:161], v[182:185], 0
	v_mfma_f32_16x16x32_bf16 v[98:101], v[166:169], v[182:185], 0
	v_mfma_f32_16x16x32_bf16 v[90:93], v[158:161], v[190:193], 0
	v_mfma_f32_16x16x32_bf16 v[82:85], v[166:169], v[190:193], 0
	v_mfma_f32_16x16x32_bf16 v[74:77], v[158:161], v[198:201], 0
	v_mfma_f32_16x16x32_bf16 v[66:69], v[166:169], v[198:201], 0
	v_mfma_f32_16x16x32_bf16 v[122:125], v[162:165], v[178:181], v[122:125]
	v_mfma_f32_16x16x32_bf16 v[114:117], v[170:173], v[178:181], v[114:117]
	v_mfma_f32_16x16x32_bf16 v[106:109], v[162:165], v[186:189], v[106:109]
	v_mfma_f32_16x16x32_bf16 v[98:101], v[170:173], v[186:189], v[98:101]
	v_mfma_f32_16x16x32_bf16 v[90:93], v[162:165], v[194:197], v[90:93]
	v_mfma_f32_16x16x32_bf16 v[82:85], v[170:173], v[194:197], v[82:85]
	v_mfma_f32_16x16x32_bf16 v[74:77], v[162:165], v[202:205], v[74:77]
	v_mfma_f32_16x16x32_bf16 v[66:69], v[170:173], v[202:205], v[66:69]
	s_setprio 0
	s_barrier
	s_add_i32 s61, s61, s81
	v_lshl_add_u64 v[206:207], s[28:29], 0, v[0:1]
	s_mov_b32 m0, s61
	ds_read_b128 v[174:177], v140 offset:16384
	ds_read_b128 v[178:181], v140 offset:17408
	ds_read_b128 v[182:185], v140 offset:18432
	ds_read_b128 v[186:189], v140 offset:19456
	ds_read_b128 v[190:193], v140 offset:20480
	ds_read_b128 v[194:197], v140 offset:21504
	ds_read_b128 v[198:201], v140 offset:22528
	ds_read_b128 v[202:205], v140 offset:23552
	global_load_lds_dwordx4 v[206:207], off
	s_add_i32 m0, s61, 0x2000
	s_add_u32 s84, s28, 0x80000
	v_lshl_add_u64 v[208:209], s[28:29], 0, v[130:131]
	s_addc_u32 s85, s29, 0
	s_add_i32 s61, s73, s81
	global_load_lds_dwordx4 v[208:209], off
	v_lshl_add_u64 v[210:211], s[84:85], 0, v[0:1]
	s_mov_b32 m0, s61
	v_lshl_add_u64 v[212:213], s[30:31], 0, v[130:131]
	global_load_lds_dwordx4 v[210:211], off
	v_lshl_add_u64 v[210:211], s[84:85], 0, v[130:131]
	s_add_i32 m0, s61, 0x2000
	s_nop 0
	global_load_lds_dwordx4 v[210:211], off
	v_lshl_add_u64 v[210:211], s[30:31], 0, v[0:1]
	s_mov_b32 m0, s82
	s_nop 0
	global_load_lds_dwordx4 v[210:211], off
	s_mov_b32 m0, s68
	s_nop 0
	global_load_lds_dwordx4 v[212:213], off
	s_waitcnt vmcnt(8)
	s_waitcnt lgkmcnt(0)
	s_barrier
	s_setprio 1
	s_waitcnt lgkmcnt(0)
	v_mfma_f32_16x16x32_bf16 v[62:65], v[142:145], v[174:177], 0
	v_mfma_f32_16x16x32_bf16 v[54:57], v[150:153], v[174:177], 0
	v_mfma_f32_16x16x32_bf16 v[46:49], v[142:145], v[182:185], 0
	v_mfma_f32_16x16x32_bf16 v[38:41], v[150:153], v[182:185], 0
	v_mfma_f32_16x16x32_bf16 v[30:33], v[142:145], v[190:193], 0
	v_mfma_f32_16x16x32_bf16 v[22:25], v[150:153], v[190:193], 0
	v_mfma_f32_16x16x32_bf16 v[14:17], v[142:145], v[198:201], 0
	v_mfma_f32_16x16x32_bf16 v[6:9], v[150:153], v[198:201], 0
	v_mfma_f32_16x16x32_bf16 v[62:65], v[146:149], v[178:181], v[62:65]
	v_mfma_f32_16x16x32_bf16 v[54:57], v[154:157], v[178:181], v[54:57]
	v_mfma_f32_16x16x32_bf16 v[46:49], v[146:149], v[186:189], v[46:49]
	v_mfma_f32_16x16x32_bf16 v[38:41], v[154:157], v[186:189], v[38:41]
	v_mfma_f32_16x16x32_bf16 v[30:33], v[146:149], v[194:197], v[30:33]
	v_mfma_f32_16x16x32_bf16 v[22:25], v[154:157], v[194:197], v[22:25]
	v_mfma_f32_16x16x32_bf16 v[14:17], v[146:149], v[202:205], v[14:17]
	v_mfma_f32_16x16x32_bf16 v[6:9], v[154:157], v[202:205], v[6:9]
	s_setprio 0
	s_setprio 1
	v_mfma_f32_16x16x32_bf16 v[58:61], v[158:161], v[174:177], 0
	v_mfma_f32_16x16x32_bf16 v[50:53], v[166:169], v[174:177], 0
	v_mfma_f32_16x16x32_bf16 v[42:45], v[158:161], v[182:185], 0
	v_mfma_f32_16x16x32_bf16 v[34:37], v[166:169], v[182:185], 0
	v_mfma_f32_16x16x32_bf16 v[26:29], v[158:161], v[190:193], 0
	v_mfma_f32_16x16x32_bf16 v[18:21], v[166:169], v[190:193], 0
	v_mfma_f32_16x16x32_bf16 v[10:13], v[158:161], v[198:201], 0
	v_mfma_f32_16x16x32_bf16 v[2:5], v[166:169], v[198:201], 0
	v_mfma_f32_16x16x32_bf16 v[58:61], v[162:165], v[178:181], v[58:61]
	v_mfma_f32_16x16x32_bf16 v[50:53], v[170:173], v[178:181], v[50:53]
	v_mfma_f32_16x16x32_bf16 v[42:45], v[162:165], v[186:189], v[42:45]
	v_mfma_f32_16x16x32_bf16 v[34:37], v[170:173], v[186:189], v[34:37]
	v_mfma_f32_16x16x32_bf16 v[26:29], v[162:165], v[194:197], v[26:29]
	v_mfma_f32_16x16x32_bf16 v[18:21], v[170:173], v[194:197], v[18:21]
	v_mfma_f32_16x16x32_bf16 v[10:13], v[162:165], v[202:205], v[10:13]
	v_mfma_f32_16x16x32_bf16 v[2:5], v[170:173], v[202:205], v[2:5]
	s_setprio 0
	s_barrier
	s_add_i32 s61, 0, 0x18000
	v_add_u32_e32 v141, s61, v138
	s_add_i32 s73, 0, 0x1c000
	ds_read_b128 v[142:145], v141
	ds_read_b128 v[146:149], v141 offset:1024
	ds_read_b128 v[150:153], v141 offset:2048
	ds_read_b128 v[154:157], v141 offset:3072
	v_add_u32_e32 v141, s73, v138
	ds_read_b128 v[158:161], v141
	ds_read_b128 v[162:165], v141 offset:1024
	ds_read_b128 v[166:169], v141 offset:2048
	ds_read_b128 v[170:173], v141 offset:3072
	s_add_u32 s30, s30, 0x80000
	s_addc_u32 s31, s31, 0
	s_mov_b32 m0, s69
	v_lshl_add_u64 v[214:215], s[30:31], 0, v[0:1]
	ds_read_b128 v[174:177], v140 offset:32768
	ds_read_b128 v[178:181], v140 offset:33792
	ds_read_b128 v[182:185], v140 offset:34816
	ds_read_b128 v[186:189], v140 offset:35840
	ds_read_b128 v[190:193], v140 offset:36864
	ds_read_b128 v[194:197], v140 offset:37888
	ds_read_b128 v[198:201], v140 offset:38912
	ds_read_b128 v[202:205], v140 offset:39936
	global_load_lds_dwordx4 v[214:215], off
	v_lshl_add_u64 v[214:215], s[30:31], 0, v[130:131]
	s_mov_b32 m0, s70
	s_nop 0
	global_load_lds_dwordx4 v[214:215], off
	s_waitcnt vmcnt(8)
	s_waitcnt lgkmcnt(0)
	s_barrier
	s_setprio 1
	s_waitcnt lgkmcnt(0)
	v_mfma_f32_16x16x32_bf16 v[126:129], v[142:145], v[174:177], v[126:129]
	v_mfma_f32_16x16x32_bf16 v[118:121], v[150:153], v[174:177], v[118:121]
	v_mfma_f32_16x16x32_bf16 v[110:113], v[142:145], v[182:185], v[110:113]
	v_mfma_f32_16x16x32_bf16 v[102:105], v[150:153], v[182:185], v[102:105]
	v_mfma_f32_16x16x32_bf16 v[94:97], v[142:145], v[190:193], v[94:97]
	v_mfma_f32_16x16x32_bf16 v[86:89], v[150:153], v[190:193], v[86:89]
	v_mfma_f32_16x16x32_bf16 v[78:81], v[142:145], v[198:201], v[78:81]
	v_mfma_f32_16x16x32_bf16 v[70:73], v[150:153], v[198:201], v[70:73]
	v_mfma_f32_16x16x32_bf16 v[126:129], v[146:149], v[178:181], v[126:129]
	v_mfma_f32_16x16x32_bf16 v[118:121], v[154:157], v[178:181], v[118:121]
	v_mfma_f32_16x16x32_bf16 v[110:113], v[146:149], v[186:189], v[110:113]
	v_mfma_f32_16x16x32_bf16 v[102:105], v[154:157], v[186:189], v[102:105]
	v_mfma_f32_16x16x32_bf16 v[94:97], v[146:149], v[194:197], v[94:97]
	v_mfma_f32_16x16x32_bf16 v[86:89], v[154:157], v[194:197], v[86:89]
	v_mfma_f32_16x16x32_bf16 v[78:81], v[146:149], v[202:205], v[78:81]
	v_mfma_f32_16x16x32_bf16 v[70:73], v[154:157], v[202:205], v[70:73]
	s_setprio 0
	s_setprio 1
	v_mfma_f32_16x16x32_bf16 v[122:125], v[158:161], v[174:177], v[122:125]
	v_mfma_f32_16x16x32_bf16 v[114:117], v[166:169], v[174:177], v[114:117]
	v_mfma_f32_16x16x32_bf16 v[106:109], v[158:161], v[182:185], v[106:109]
	v_mfma_f32_16x16x32_bf16 v[98:101], v[166:169], v[182:185], v[98:101]
	v_mfma_f32_16x16x32_bf16 v[90:93], v[158:161], v[190:193], v[90:93]
	v_mfma_f32_16x16x32_bf16 v[82:85], v[166:169], v[190:193], v[82:85]
	v_mfma_f32_16x16x32_bf16 v[74:77], v[158:161], v[198:201], v[74:77]
	v_mfma_f32_16x16x32_bf16 v[66:69], v[166:169], v[198:201], v[66:69]
	v_mfma_f32_16x16x32_bf16 v[122:125], v[162:165], v[178:181], v[122:125]
	v_mfma_f32_16x16x32_bf16 v[114:117], v[170:173], v[178:181], v[114:117]
	v_mfma_f32_16x16x32_bf16 v[106:109], v[162:165], v[186:189], v[106:109]
	v_mfma_f32_16x16x32_bf16 v[98:101], v[170:173], v[186:189], v[98:101]
	v_mfma_f32_16x16x32_bf16 v[90:93], v[162:165], v[194:197], v[90:93]
	v_mfma_f32_16x16x32_bf16 v[82:85], v[170:173], v[194:197], v[82:85]
	v_mfma_f32_16x16x32_bf16 v[74:77], v[162:165], v[202:205], v[74:77]
	v_mfma_f32_16x16x32_bf16 v[66:69], v[170:173], v[202:205], v[66:69]
	s_setprio 0
	s_barrier
	s_add_i32 s30, s61, s81
	v_lshl_add_u64 v[206:207], v[206:207], 0, s[54:55]
	s_mov_b32 m0, s30
	ds_read_b128 v[174:177], v140 offset:49152
	ds_read_b128 v[178:181], v140 offset:50176
	ds_read_b128 v[182:185], v140 offset:51200
	ds_read_b128 v[186:189], v140 offset:52224
	ds_read_b128 v[190:193], v140 offset:53248
	ds_read_b128 v[194:197], v140 offset:54272
	ds_read_b128 v[198:201], v140 offset:55296
	ds_read_b128 v[202:205], v140 offset:56320
	global_load_lds_dwordx4 v[206:207], off
	s_add_i32 m0, s30, 0x2000
	s_add_u32 s28, s28, 0x80080
	v_lshl_add_u64 v[206:207], v[208:209], 0, s[54:55]
	s_addc_u32 s29, s29, 0
	s_add_i32 s30, s73, s81
	global_load_lds_dwordx4 v[206:207], off
	v_lshl_add_u64 v[206:207], s[28:29], 0, v[0:1]
	s_mov_b32 m0, s30
	s_nop 0
	global_load_lds_dwordx4 v[206:207], off
	v_lshl_add_u64 v[206:207], s[28:29], 0, v[130:131]
	s_add_i32 m0, s30, 0x2000
	s_nop 0
	global_load_lds_dwordx4 v[206:207], off
	v_lshl_add_u64 v[206:207], v[210:211], 0, s[54:55]
	s_mov_b32 m0, s71
	s_nop 0
	global_load_lds_dwordx4 v[206:207], off
	v_lshl_add_u64 v[206:207], v[212:213], 0, s[54:55]
	s_mov_b32 m0, s72
	s_nop 0
	global_load_lds_dwordx4 v[206:207], off
	s_waitcnt vmcnt(8)
	s_waitcnt lgkmcnt(0)
	s_barrier
	s_setprio 1
	s_waitcnt lgkmcnt(0)
	v_mfma_f32_16x16x32_bf16 v[62:65], v[142:145], v[174:177], v[62:65]
	v_mfma_f32_16x16x32_bf16 v[54:57], v[150:153], v[174:177], v[54:57]
	v_mfma_f32_16x16x32_bf16 v[46:49], v[142:145], v[182:185], v[46:49]
	v_mfma_f32_16x16x32_bf16 v[38:41], v[150:153], v[182:185], v[38:41]
	v_mfma_f32_16x16x32_bf16 v[30:33], v[142:145], v[190:193], v[30:33]
	v_mfma_f32_16x16x32_bf16 v[22:25], v[150:153], v[190:193], v[22:25]
	v_mfma_f32_16x16x32_bf16 v[14:17], v[142:145], v[198:201], v[14:17]
	v_mfma_f32_16x16x32_bf16 v[6:9], v[150:153], v[198:201], v[6:9]
	v_mfma_f32_16x16x32_bf16 v[62:65], v[146:149], v[178:181], v[62:65]
	v_mfma_f32_16x16x32_bf16 v[54:57], v[154:157], v[178:181], v[54:57]
	v_mfma_f32_16x16x32_bf16 v[46:49], v[146:149], v[186:189], v[46:49]
	v_mfma_f32_16x16x32_bf16 v[38:41], v[154:157], v[186:189], v[38:41]
	v_mfma_f32_16x16x32_bf16 v[30:33], v[146:149], v[194:197], v[30:33]
	v_mfma_f32_16x16x32_bf16 v[22:25], v[154:157], v[194:197], v[22:25]
	v_mfma_f32_16x16x32_bf16 v[14:17], v[146:149], v[202:205], v[14:17]
	v_mfma_f32_16x16x32_bf16 v[6:9], v[154:157], v[202:205], v[6:9]
	s_setprio 0
	s_setprio 1
	v_mfma_f32_16x16x32_bf16 v[58:61], v[158:161], v[174:177], v[58:61]
	v_mfma_f32_16x16x32_bf16 v[50:53], v[166:169], v[174:177], v[50:53]
	v_mfma_f32_16x16x32_bf16 v[42:45], v[158:161], v[182:185], v[42:45]
	v_mfma_f32_16x16x32_bf16 v[34:37], v[166:169], v[182:185], v[34:37]
	v_mfma_f32_16x16x32_bf16 v[26:29], v[158:161], v[190:193], v[26:29]
	v_mfma_f32_16x16x32_bf16 v[18:21], v[166:169], v[190:193], v[18:21]
	v_mfma_f32_16x16x32_bf16 v[10:13], v[158:161], v[198:201], v[10:13]
	v_mfma_f32_16x16x32_bf16 v[2:5], v[166:169], v[198:201], v[2:5]
	v_mfma_f32_16x16x32_bf16 v[58:61], v[162:165], v[178:181], v[58:61]
	v_mfma_f32_16x16x32_bf16 v[50:53], v[170:173], v[178:181], v[50:53]
	v_mfma_f32_16x16x32_bf16 v[42:45], v[162:165], v[186:189], v[42:45]
	v_mfma_f32_16x16x32_bf16 v[34:37], v[170:173], v[186:189], v[34:37]
	v_mfma_f32_16x16x32_bf16 v[26:29], v[162:165], v[194:197], v[26:29]
	v_mfma_f32_16x16x32_bf16 v[18:21], v[170:173], v[194:197], v[18:21]
	v_mfma_f32_16x16x32_bf16 v[10:13], v[162:165], v[202:205], v[10:13]
	v_mfma_f32_16x16x32_bf16 v[2:5], v[170:173], v[202:205], v[2:5]
	s_setprio 0
	s_barrier
	s_add_i32 s49, s49, 2
	s_add_u32 s45, s45, 0x100
	s_addc_u32 s48, s48, 0
	s_add_u32 s26, s26, 0x100
	s_addc_u32 s27, s27, 0
	s_cmp_gt_u32 s49, 29
	s_cbranch_scc1 .Lpeel_exit_G3

.LBB0_1063:
	v_mul_f32_e32 v144, 0xbfb8aa3b, v126
	v_exp_f32_e32 v144, v144
	v_lshl_or_b32 v142, s25, 7, v139
	v_lshl_add_u32 v141, s24, 8, v137
	v_ashrrev_i32_e32 v143, 31, v142
	v_add_f32_e32 v144, 1.0, v144
	v_rcp_f32_e32 v144, v144
	s_andn2_b64 vcc, exec, s[4:5]
	v_mul_f32_e32 v126, v126, v144
	v_mul_f32_e32 v122, v126, v122
	v_mul_f32_e32 v126, 0xbfb8aa3b, v127
	v_exp_f32_e32 v126, v126
	s_nop 0
	v_add_f32_e32 v126, 1.0, v126
	v_rcp_f32_e32 v126, v126
	s_nop 0
	v_mul_f32_e32 v126, v127, v126
	v_mul_f32_e32 v123, v126, v123
	v_mul_f32_e32 v126, 0xbfb8aa3b, v128
	v_exp_f32_e32 v126, v126
	s_nop 0
	v_add_f32_e32 v126, 1.0, v126
	v_rcp_f32_e32 v126, v126
	s_nop 0
	v_mul_f32_e32 v126, v128, v126
	v_mul_f32_e32 v124, v126, v124
	v_mul_f32_e32 v126, 0xbfb8aa3b, v129
	v_exp_f32_e32 v126, v126
	s_nop 0
	v_add_f32_e32 v126, 1.0, v126
	v_rcp_f32_e32 v126, v126
	s_nop 0
	v_mul_f32_e32 v126, v129, v126
	v_mul_f32_e32 v125, v126, v125
	v_mul_f32_e32 v126, 0xbfb8aa3b, v118
	v_exp_f32_e32 v126, v126
	s_nop 0
	v_add_f32_e32 v126, 1.0, v126
	v_rcp_f32_e32 v126, v126
	s_nop 0
	v_mul_f32_e32 v118, v118, v126
	v_mul_f32_e32 v114, v118, v114
	v_mul_f32_e32 v118, 0xbfb8aa3b, v119
	v_exp_f32_e32 v118, v118
	s_nop 0
	v_add_f32_e32 v118, 1.0, v118
	v_rcp_f32_e32 v118, v118
	s_nop 0
	v_mul_f32_e32 v118, v119, v118
	v_mul_f32_e32 v115, v118, v115
	v_mul_f32_e32 v118, 0xbfb8aa3b, v120
	v_exp_f32_e32 v118, v118
	s_nop 0
	v_add_f32_e32 v118, 1.0, v118
	v_rcp_f32_e32 v118, v118
	s_nop 0
	v_mul_f32_e32 v118, v120, v118
	v_mul_f32_e32 v116, v118, v116
	v_mul_f32_e32 v118, 0xbfb8aa3b, v121
	v_exp_f32_e32 v118, v118
	s_nop 0
	v_add_f32_e32 v118, 1.0, v118
	v_rcp_f32_e32 v118, v118
	s_nop 0
	v_mul_f32_e32 v118, v121, v118
	v_mul_f32_e32 v117, v118, v117
	v_cvt_pk_bf16_f32 v118, v122, v123
	v_cvt_pk_bf16_f32 v119, v124, v125
	v_cvt_pk_bf16_f32 v120, v114, v115
	v_mov_b64_e32 v[114:115], s[10:11]
	v_cvt_pk_bf16_f32 v121, v116, v117
	v_mad_i64_i32 v[122:123], s[24:25], v141, s53, v[114:115]
	v_lshlrev_b64 v[116:117], 1, v[142:143]
	v_lshl_add_u64 v[122:123], v[122:123], 0, v[116:117]
	global_store_dwordx4 v[122:123], v[118:121], off
	s_nop 1
	v_mul_f32_e32 v118, 0xbfb8aa3b, v110
	v_exp_f32_e32 v118, v118
	s_nop 0
	v_add_f32_e32 v118, 1.0, v118
	v_rcp_f32_e32 v118, v118
	s_nop 0
	v_mul_f32_e32 v110, v110, v118
	v_mul_f32_e32 v106, v110, v106
	v_mul_f32_e32 v110, 0xbfb8aa3b, v111
	v_exp_f32_e32 v110, v110
	s_nop 0
	v_add_f32_e32 v110, 1.0, v110
	v_rcp_f32_e32 v110, v110
	s_nop 0
	v_mul_f32_e32 v110, v111, v110
	v_mul_f32_e32 v107, v110, v107
	v_mul_f32_e32 v110, 0xbfb8aa3b, v112
	v_exp_f32_e32 v110, v110
	s_nop 0
	v_add_f32_e32 v110, 1.0, v110
	v_rcp_f32_e32 v110, v110
	s_nop 0
	v_mul_f32_e32 v110, v112, v110
	v_mul_f32_e32 v108, v110, v108
	v_mul_f32_e32 v110, 0xbfb8aa3b, v113
	v_exp_f32_e32 v110, v110
	s_nop 0
	v_add_f32_e32 v110, 1.0, v110
	v_rcp_f32_e32 v110, v110
	s_nop 0
	v_mul_f32_e32 v110, v113, v110
	v_mul_f32_e32 v109, v110, v109
	v_mul_f32_e32 v110, 0xbfb8aa3b, v102
	v_exp_f32_e32 v110, v110
	s_nop 0
	v_add_f32_e32 v110, 1.0, v110
	v_rcp_f32_e32 v110, v110
	s_nop 0
	v_mul_f32_e32 v102, v102, v110
	v_mul_f32_e32 v102, v102, v98
	v_mul_f32_e32 v98, 0xbfb8aa3b, v103
	v_exp_f32_e32 v98, v98
	s_nop 0
	v_add_f32_e32 v98, 1.0, v98
	v_rcp_f32_e32 v98, v98
	s_nop 0
	v_mul_f32_e32 v98, v103, v98
	v_mul_f32_e32 v103, v98, v99
	v_mul_f32_e32 v98, 0xbfb8aa3b, v104
	v_exp_f32_e32 v98, v98
	s_nop 0
	v_add_f32_e32 v98, 1.0, v98
	v_rcp_f32_e32 v98, v98
	s_nop 0
	v_mul_f32_e32 v98, v104, v98
	v_mul_f32_e32 v104, v98, v100
	v_mul_f32_e32 v98, 0xbfb8aa3b, v105
	v_exp_f32_e32 v98, v98
	s_nop 0
	v_add_f32_e32 v98, 1.0, v98
	v_rcp_f32_e32 v98, v98
	s_nop 0
	v_mul_f32_e32 v98, v105, v98
	v_or_b32_e32 v105, 16, v141
	v_mul_f32_e32 v101, v98, v101
	v_cvt_pk_bf16_f32 v98, v106, v107
	v_cvt_pk_bf16_f32 v99, v108, v109
	v_cvt_pk_bf16_f32 v100, v102, v103
	v_mad_i64_i32 v[102:103], s[24:25], v105, s53, v[114:115]
	v_lshl_add_u64 v[102:103], v[102:103], 0, v[116:117]
	v_cvt_pk_bf16_f32 v101, v104, v101
	global_store_dwordx4 v[102:103], v[98:101], off
	s_nop 1
	v_mul_f32_e32 v98, 0xbfb8aa3b, v94
	v_exp_f32_e32 v98, v98
	s_nop 0
	v_add_f32_e32 v98, 1.0, v98
	v_rcp_f32_e32 v98, v98
	s_nop 0
	v_mul_f32_e32 v94, v94, v98
	v_mul_f32_e32 v90, v94, v90
	v_mul_f32_e32 v94, 0xbfb8aa3b, v95
	v_exp_f32_e32 v94, v94
	s_nop 0
	v_add_f32_e32 v94, 1.0, v94
	v_rcp_f32_e32 v94, v94
	s_nop 0
	v_mul_f32_e32 v94, v95, v94
	v_mul_f32_e32 v91, v94, v91
	v_mul_f32_e32 v94, 0xbfb8aa3b, v96
	v_exp_f32_e32 v94, v94
	s_nop 0
	v_add_f32_e32 v94, 1.0, v94
	v_rcp_f32_e32 v94, v94
	s_nop 0
	v_mul_f32_e32 v94, v96, v94
	v_mul_f32_e32 v92, v94, v92
	v_mul_f32_e32 v94, 0xbfb8aa3b, v97
	v_exp_f32_e32 v94, v94
	s_nop 0
	v_add_f32_e32 v94, 1.0, v94
	v_rcp_f32_e32 v94, v94
	s_nop 0
	v_mul_f32_e32 v94, v97, v94
	v_mul_f32_e32 v93, v94, v93
	v_mul_f32_e32 v94, 0xbfb8aa3b, v86
	v_exp_f32_e32 v94, v94
	s_nop 0
	v_add_f32_e32 v94, 1.0, v94
	v_rcp_f32_e32 v94, v94
	s_nop 0
	v_mul_f32_e32 v86, v86, v94
	v_mul_f32_e32 v86, v86, v82
	v_mul_f32_e32 v82, 0xbfb8aa3b, v87
	v_exp_f32_e32 v82, v82
	s_nop 0
	v_add_f32_e32 v82, 1.0, v82
	v_rcp_f32_e32 v82, v82
	s_nop 0
	v_mul_f32_e32 v82, v87, v82
	v_mul_f32_e32 v87, v82, v83
	v_mul_f32_e32 v82, 0xbfb8aa3b, v88
	v_exp_f32_e32 v82, v82
	s_nop 0
	v_add_f32_e32 v82, 1.0, v82
	v_rcp_f32_e32 v82, v82
	s_nop 0
	v_mul_f32_e32 v82, v88, v82
	v_mul_f32_e32 v88, v82, v84
	v_mul_f32_e32 v82, 0xbfb8aa3b, v89
	v_exp_f32_e32 v82, v82
	s_nop 0
	v_add_f32_e32 v82, 1.0, v82
	v_rcp_f32_e32 v82, v82
	s_nop 0
	v_mul_f32_e32 v82, v89, v82
	v_or_b32_e32 v89, 32, v141
	v_mul_f32_e32 v85, v82, v85
	v_cvt_pk_bf16_f32 v82, v90, v91
	v_cvt_pk_bf16_f32 v83, v92, v93
	v_cvt_pk_bf16_f32 v84, v86, v87
	v_mad_i64_i32 v[86:87], s[24:25], v89, s53, v[114:115]
	v_lshl_add_u64 v[86:87], v[86:87], 0, v[116:117]
	v_cvt_pk_bf16_f32 v85, v88, v85
	global_store_dwordx4 v[86:87], v[82:85], off
	s_nop 1
	v_mul_f32_e32 v82, 0xbfb8aa3b, v78
	v_exp_f32_e32 v82, v82
	s_nop 0
	v_add_f32_e32 v82, 1.0, v82
	v_rcp_f32_e32 v82, v82
	s_nop 0
	v_mul_f32_e32 v78, v78, v82
	v_mul_f32_e32 v74, v78, v74
	v_mul_f32_e32 v78, 0xbfb8aa3b, v79
	v_exp_f32_e32 v78, v78
	s_nop 0
	v_add_f32_e32 v78, 1.0, v78
	v_rcp_f32_e32 v78, v78
	s_nop 0
	v_mul_f32_e32 v78, v79, v78
	v_mul_f32_e32 v75, v78, v75
	v_mul_f32_e32 v78, 0xbfb8aa3b, v80
	v_exp_f32_e32 v78, v78
	s_nop 0
	v_add_f32_e32 v78, 1.0, v78
	v_rcp_f32_e32 v78, v78
	s_nop 0
	v_mul_f32_e32 v78, v80, v78
	v_mul_f32_e32 v76, v78, v76
	v_mul_f32_e32 v78, 0xbfb8aa3b, v81
	v_exp_f32_e32 v78, v78
	s_nop 0
	v_add_f32_e32 v78, 1.0, v78
	v_rcp_f32_e32 v78, v78
	s_nop 0
	v_mul_f32_e32 v78, v81, v78
	v_mul_f32_e32 v77, v78, v77
	v_mul_f32_e32 v78, 0xbfb8aa3b, v70
	v_exp_f32_e32 v78, v78
	s_nop 0
	v_add_f32_e32 v78, 1.0, v78
	v_rcp_f32_e32 v78, v78
	s_nop 0
	v_mul_f32_e32 v70, v70, v78
	v_mul_f32_e32 v70, v70, v66
	v_mul_f32_e32 v66, 0xbfb8aa3b, v71
	v_exp_f32_e32 v66, v66
	s_nop 0
	v_add_f32_e32 v66, 1.0, v66
	v_rcp_f32_e32 v66, v66
	s_nop 0
	v_mul_f32_e32 v66, v71, v66
	v_mul_f32_e32 v71, v66, v67
	v_mul_f32_e32 v66, 0xbfb8aa3b, v72
	v_exp_f32_e32 v66, v66
	s_nop 0
	v_add_f32_e32 v66, 1.0, v66
	v_rcp_f32_e32 v66, v66
	s_nop 0
	v_mul_f32_e32 v66, v72, v66
	v_mul_f32_e32 v72, v66, v68
	v_mul_f32_e32 v66, 0xbfb8aa3b, v73
	v_exp_f32_e32 v66, v66
	s_nop 0
	v_add_f32_e32 v66, 1.0, v66
	v_rcp_f32_e32 v66, v66
	s_nop 0
	v_mul_f32_e32 v66, v73, v66
	v_or_b32_e32 v73, 48, v141
	v_mul_f32_e32 v69, v66, v69
	v_cvt_pk_bf16_f32 v66, v74, v75
	v_cvt_pk_bf16_f32 v67, v76, v77
	v_cvt_pk_bf16_f32 v68, v70, v71
	v_mad_i64_i32 v[70:71], s[24:25], v73, s53, v[114:115]
	v_lshl_add_u64 v[70:71], v[70:71], 0, v[116:117]
	v_cvt_pk_bf16_f32 v69, v72, v69
	global_store_dwordx4 v[70:71], v[66:69], off
	s_nop 1
	v_mul_f32_e32 v67, 0xbfb8aa3b, v62
	v_exp_f32_e32 v67, v67
	v_add_u32_e32 v66, 0x80, v141
	v_add_f32_e32 v67, 1.0, v67
	v_rcp_f32_e32 v67, v67
	s_nop 0
	v_mul_f32_e32 v62, v62, v67
	v_mul_f32_e32 v58, v62, v58
	v_mul_f32_e32 v62, 0xbfb8aa3b, v63
	v_exp_f32_e32 v62, v62
	s_nop 0
	v_add_f32_e32 v62, 1.0, v62
	v_rcp_f32_e32 v62, v62
	s_nop 0
	v_mul_f32_e32 v62, v63, v62
	v_mul_f32_e32 v59, v62, v59
	v_mul_f32_e32 v62, 0xbfb8aa3b, v64
	v_exp_f32_e32 v62, v62
	s_nop 0
	v_add_f32_e32 v62, 1.0, v62
	v_rcp_f32_e32 v62, v62
	s_nop 0
	v_mul_f32_e32 v62, v64, v62
	v_mul_f32_e32 v60, v62, v60
	v_mul_f32_e32 v62, 0xbfb8aa3b, v65
	v_exp_f32_e32 v62, v62
	s_nop 0
	v_add_f32_e32 v62, 1.0, v62
	v_rcp_f32_e32 v62, v62
	s_nop 0
	v_mul_f32_e32 v62, v65, v62
	v_mul_f32_e32 v61, v62, v61
	v_mul_f32_e32 v62, 0xbfb8aa3b, v54
	v_exp_f32_e32 v62, v62
	s_nop 0
	v_add_f32_e32 v62, 1.0, v62
	v_rcp_f32_e32 v62, v62
	s_nop 0
	v_mul_f32_e32 v54, v54, v62
	v_mul_f32_e32 v54, v54, v50
	v_mul_f32_e32 v50, 0xbfb8aa3b, v55
	v_exp_f32_e32 v50, v50
	s_nop 0
	v_add_f32_e32 v50, 1.0, v50
	v_rcp_f32_e32 v50, v50
	s_nop 0
	v_mul_f32_e32 v50, v55, v50
	v_mul_f32_e32 v55, v50, v51
	v_mul_f32_e32 v50, 0xbfb8aa3b, v56
	v_exp_f32_e32 v50, v50
	s_nop 0
	v_add_f32_e32 v50, 1.0, v50
	v_rcp_f32_e32 v50, v50
	s_nop 0
	v_mul_f32_e32 v50, v56, v50
	v_mul_f32_e32 v56, v50, v52
	v_mul_f32_e32 v50, 0xbfb8aa3b, v57
	v_exp_f32_e32 v50, v50
	s_nop 0
	v_add_f32_e32 v50, 1.0, v50
	v_rcp_f32_e32 v50, v50
	s_nop 0
	v_mul_f32_e32 v50, v57, v50
	v_mul_f32_e32 v53, v50, v53
	v_cvt_pk_bf16_f32 v50, v58, v59
	v_cvt_pk_bf16_f32 v51, v60, v61
	v_cvt_pk_bf16_f32 v52, v54, v55
	v_mad_i64_i32 v[54:55], s[24:25], v66, s53, v[114:115]
	v_lshl_add_u64 v[54:55], v[54:55], 0, v[116:117]
	v_cvt_pk_bf16_f32 v53, v56, v53
	global_store_dwordx4 v[54:55], v[50:53], off
	s_nop 1
	v_mul_f32_e32 v50, 0xbfb8aa3b, v46
	v_exp_f32_e32 v50, v50
	s_nop 0
	v_add_f32_e32 v50, 1.0, v50
	v_rcp_f32_e32 v50, v50
	s_nop 0
	v_mul_f32_e32 v46, v46, v50
	v_mul_f32_e32 v42, v46, v42
	v_mul_f32_e32 v46, 0xbfb8aa3b, v47
	v_exp_f32_e32 v46, v46
	s_nop 0
	v_add_f32_e32 v46, 1.0, v46
	v_rcp_f32_e32 v46, v46
	s_nop 0
	v_mul_f32_e32 v46, v47, v46
	v_mul_f32_e32 v43, v46, v43
	v_mul_f32_e32 v46, 0xbfb8aa3b, v48
	v_exp_f32_e32 v46, v46
	s_nop 0
	v_add_f32_e32 v46, 1.0, v46
	v_rcp_f32_e32 v46, v46
	s_nop 0
	v_mul_f32_e32 v46, v48, v46
	v_mul_f32_e32 v44, v46, v44
	v_mul_f32_e32 v46, 0xbfb8aa3b, v49
	v_exp_f32_e32 v46, v46
	s_nop 0
	v_add_f32_e32 v46, 1.0, v46
	v_rcp_f32_e32 v46, v46
	s_nop 0
	v_mul_f32_e32 v46, v49, v46
	v_mul_f32_e32 v45, v46, v45
	v_mul_f32_e32 v46, 0xbfb8aa3b, v38
	v_exp_f32_e32 v46, v46
	s_nop 0
	v_add_f32_e32 v46, 1.0, v46
	v_rcp_f32_e32 v46, v46
	s_nop 0
	v_mul_f32_e32 v38, v38, v46
	v_mul_f32_e32 v38, v38, v34
	v_mul_f32_e32 v34, 0xbfb8aa3b, v39
	v_exp_f32_e32 v34, v34
	s_nop 0
	v_add_f32_e32 v34, 1.0, v34
	v_rcp_f32_e32 v34, v34
	s_nop 0
	v_mul_f32_e32 v34, v39, v34
	v_mul_f32_e32 v39, v34, v35
	v_mul_f32_e32 v34, 0xbfb8aa3b, v40
	v_exp_f32_e32 v34, v34
	s_nop 0
	v_add_f32_e32 v34, 1.0, v34
	v_rcp_f32_e32 v34, v34
	s_nop 0
	v_mul_f32_e32 v34, v40, v34
	v_mul_f32_e32 v40, v34, v36
	v_mul_f32_e32 v34, 0xbfb8aa3b, v41
	v_exp_f32_e32 v34, v34
	s_nop 0
	v_add_f32_e32 v34, 1.0, v34
	v_rcp_f32_e32 v34, v34
	s_nop 0
	v_mul_f32_e32 v34, v41, v34
	v_add_u32_e32 v41, 0x90, v141
	v_mul_f32_e32 v37, v34, v37
	v_cvt_pk_bf16_f32 v34, v42, v43
	v_cvt_pk_bf16_f32 v35, v44, v45
	v_cvt_pk_bf16_f32 v36, v38, v39
	v_mad_i64_i32 v[38:39], s[24:25], v41, s53, v[114:115]
	v_lshl_add_u64 v[38:39], v[38:39], 0, v[116:117]
	v_cvt_pk_bf16_f32 v37, v40, v37
	global_store_dwordx4 v[38:39], v[34:37], off
	s_nop 1
	v_mul_f32_e32 v34, 0xbfb8aa3b, v30
	v_exp_f32_e32 v34, v34
	s_nop 0
	v_add_f32_e32 v34, 1.0, v34
	v_rcp_f32_e32 v34, v34
	s_nop 0
	v_mul_f32_e32 v30, v30, v34
	v_mul_f32_e32 v26, v30, v26
	v_mul_f32_e32 v30, 0xbfb8aa3b, v31
	v_exp_f32_e32 v30, v30
	s_nop 0
	v_add_f32_e32 v30, 1.0, v30
	v_rcp_f32_e32 v30, v30
	s_nop 0
	v_mul_f32_e32 v30, v31, v30
	v_mul_f32_e32 v27, v30, v27
	v_mul_f32_e32 v30, 0xbfb8aa3b, v32
	v_exp_f32_e32 v30, v30
	s_nop 0
	v_add_f32_e32 v30, 1.0, v30
	v_rcp_f32_e32 v30, v30
	s_nop 0
	v_mul_f32_e32 v30, v32, v30
	v_mul_f32_e32 v28, v30, v28
	v_mul_f32_e32 v30, 0xbfb8aa3b, v33
	v_exp_f32_e32 v30, v30
	s_nop 0
	v_add_f32_e32 v30, 1.0, v30
	v_rcp_f32_e32 v30, v30
	s_nop 0
	v_mul_f32_e32 v30, v33, v30
	v_mul_f32_e32 v29, v30, v29
	v_mul_f32_e32 v30, 0xbfb8aa3b, v22
	v_exp_f32_e32 v30, v30
	s_nop 0
	v_add_f32_e32 v30, 1.0, v30
	v_rcp_f32_e32 v30, v30
	s_nop 0
	v_mul_f32_e32 v22, v22, v30
	v_mul_f32_e32 v22, v22, v18
	v_mul_f32_e32 v18, 0xbfb8aa3b, v23
	v_exp_f32_e32 v18, v18
	s_nop 0
	v_add_f32_e32 v18, 1.0, v18
	v_rcp_f32_e32 v18, v18
	s_nop 0
	v_mul_f32_e32 v18, v23, v18
	v_mul_f32_e32 v23, v18, v19
	v_mul_f32_e32 v18, 0xbfb8aa3b, v24
	v_exp_f32_e32 v18, v18
	s_nop 0
	v_add_f32_e32 v18, 1.0, v18
	v_rcp_f32_e32 v18, v18
	s_nop 0
	v_mul_f32_e32 v18, v24, v18
	v_mul_f32_e32 v24, v18, v20
	v_mul_f32_e32 v18, 0xbfb8aa3b, v25
	v_exp_f32_e32 v18, v18
	s_nop 0
	v_add_f32_e32 v18, 1.0, v18
	v_rcp_f32_e32 v18, v18
	s_nop 0
	v_mul_f32_e32 v18, v25, v18
	v_add_u32_e32 v25, 0xa0, v141
	v_mul_f32_e32 v21, v18, v21
	v_cvt_pk_bf16_f32 v18, v26, v27
	v_cvt_pk_bf16_f32 v19, v28, v29
	v_cvt_pk_bf16_f32 v20, v22, v23
	v_mad_i64_i32 v[22:23], s[24:25], v25, s53, v[114:115]
	v_lshl_add_u64 v[22:23], v[22:23], 0, v[116:117]
	v_cvt_pk_bf16_f32 v21, v24, v21
	global_store_dwordx4 v[22:23], v[18:21], off
	s_nop 1
	v_mul_f32_e32 v18, 0xbfb8aa3b, v14
	v_exp_f32_e32 v18, v18
	s_nop 0
	v_add_f32_e32 v18, 1.0, v18
	v_rcp_f32_e32 v18, v18
	s_nop 0
	v_mul_f32_e32 v14, v14, v18
	v_mul_f32_e32 v10, v14, v10
	v_mul_f32_e32 v14, 0xbfb8aa3b, v15
	v_exp_f32_e32 v14, v14
	s_nop 0
	v_add_f32_e32 v14, 1.0, v14
	v_rcp_f32_e32 v14, v14
	s_nop 0
	v_mul_f32_e32 v14, v15, v14
	v_mul_f32_e32 v11, v14, v11
	v_mul_f32_e32 v14, 0xbfb8aa3b, v16
	v_exp_f32_e32 v14, v14
	s_nop 0
	v_add_f32_e32 v14, 1.0, v14
	v_rcp_f32_e32 v14, v14
	s_nop 0
	v_mul_f32_e32 v14, v16, v14
	v_mul_f32_e32 v12, v14, v12
	v_mul_f32_e32 v14, 0xbfb8aa3b, v17
	v_exp_f32_e32 v14, v14
	s_nop 0
	v_add_f32_e32 v14, 1.0, v14
	v_rcp_f32_e32 v14, v14
	s_nop 0
	v_mul_f32_e32 v14, v17, v14
	v_mul_f32_e32 v13, v14, v13
	v_mul_f32_e32 v14, 0xbfb8aa3b, v6
	v_exp_f32_e32 v14, v14
	s_nop 0
	v_add_f32_e32 v14, 1.0, v14
	v_rcp_f32_e32 v14, v14
	s_nop 0
	v_mul_f32_e32 v6, v6, v14
	v_mul_f32_e32 v6, v6, v2
	v_mul_f32_e32 v2, 0xbfb8aa3b, v7
	v_exp_f32_e32 v2, v2
	s_nop 0
	v_add_f32_e32 v2, 1.0, v2
	v_rcp_f32_e32 v2, v2
	s_nop 0
	v_mul_f32_e32 v2, v7, v2
	v_mul_f32_e32 v7, v2, v3
	v_mul_f32_e32 v2, 0xbfb8aa3b, v8
	v_exp_f32_e32 v2, v2
	s_nop 0
	v_add_f32_e32 v2, 1.0, v2
	v_rcp_f32_e32 v2, v2
	s_nop 0
	v_mul_f32_e32 v2, v8, v2
	v_mul_f32_e32 v8, v2, v4
	v_mul_f32_e32 v2, 0xbfb8aa3b, v9
	v_exp_f32_e32 v2, v2
	s_nop 0
	v_add_f32_e32 v2, 1.0, v2
	v_rcp_f32_e32 v2, v2
	s_nop 0
	v_mul_f32_e32 v2, v9, v2
	v_add_u32_e32 v9, 0xb0, v141
	v_mul_f32_e32 v5, v2, v5
	v_cvt_pk_bf16_f32 v2, v10, v11
	v_cvt_pk_bf16_f32 v3, v12, v13
	v_cvt_pk_bf16_f32 v4, v6, v7
	v_mad_i64_i32 v[6:7], s[24:25], v9, s53, v[114:115]
	v_lshl_add_u64 v[6:7], v[6:7], 0, v[116:117]
	s_mov_b64 s[24:25], -1
	v_cvt_pk_bf16_f32 v5, v8, v5
	global_store_dwordx4 v[6:7], v[2:5], off
	s_cbranch_vccnz .LBB0_1056
	s_branch .LBB0_1055
